# stack: ResAdd x_old prefetch + GEMM prologue K-tile1 loads issued before first wait + skinny-GEMM pre-loads overlapped with operand loads
# speedup vs baseline: 1.0060x; 1.0040x over previous
.LBB0_279:
	s_add_u32 s85, s62, 0x12c80000
	s_addc_u32 s86, s63, 0
	s_add_u32 s12, s62, 0x2300000
	s_addc_u32 s13, s63, 0
	v_and_b32_e32 v180, 15, v157
	s_add_u32 s2, s60, 0x2c580000
	v_lshlrev_b32_e32 v146, 2, v180
	s_addc_u32 s3, s61, 0
	s_andn2_b64 vcc, exec, s[14:15]
	s_cbranch_vccnz .LBB0_451
	s_waitcnt vmcnt(3)
	v_bfe_i32 v2, v147, 27, 1
	v_lshlrev_b32_e32 v0, 4, v147
	v_lshrrev_b32_e32 v2, 22, v2
	v_add_u32_e32 v2, v0, v2
	v_and_b32_e32 v2, 0xfffffc00, v2
	v_sub_u32_e32 v2, v0, v2
	v_ashrrev_i32_e32 v1, 31, v147
	v_lshrrev_b32_e32 v3, 4, v2
	v_lshrrev_b32_e32 v1, 26, v1
	v_bitop3_b32 v2, v3, v2, 32 bitop3:0x6c
	v_add_u32_e32 v1, v147, v1
	s_waitcnt vmcnt(2)
	v_ashrrev_i32_e32 v4, 31, v2
	v_ashrrev_i32_e32 v1, 6, v1
	v_lshrrev_b32_e32 v4, 26, v4
	v_lshlrev_b32_e32 v3, 3, v1
	v_add_u32_e32 v4, v2, v4
	v_and_b32_e32 v3, -16, v3
	v_ashrrev_i32_e32 v5, 6, v4
	v_lshlrev_b32_e32 v1, 5, v1
	v_add_u32_e32 v3, v5, v3
	s_waitcnt vmcnt(0)
	v_and_b32_e32 v12, 32, v1
	v_and_b32_e32 v1, 0xc0, v4
	v_sub_u32_e32 v1, v2, v1
	v_mov_b32_e32 v6, 1
	v_lshlrev_b32_e32 v2, 1, v3
	v_lshrrev_b32_e32 v4, 2, v3
	v_and_b32_e32 v5, 3, v5
	s_mov_b32 s6, 0x7fffffe0
	v_ashrrev_i16_sdwa v1, v6, sext(v1) dst_sel:DWORD dst_unused:UNUSED_PAD src0_sel:DWORD src1_sel:BYTE_0
	v_and_b32_e32 v2, 24, v2
	v_and_b32_e32 v4, 4, v4
	v_and_or_b32 v5, v3, s6, v5
	v_bfe_i32 v13, v1, 0, 16
	v_or3_b32 v2, v5, v4, v2
	v_add_u32_e32 v1, v12, v13
	v_mul_lo_u32 v14, s36, v3
	v_mul_lo_u32 v2, s36, v2
	v_add_u32_e32 v0, 0x2000, v0
	v_add_lshl_u32 v148, v14, v1, 1
	v_add_lshl_u32 v150, v2, v1, 1
	v_ashrrev_i32_e32 v1, 31, v0
	v_lshrrev_b32_e32 v1, 22, v1
	v_add_u32_e32 v1, v0, v1
	v_ashrrev_i32_e32 v1, 10, v1
	v_mul_i32_i24_e32 v2, 0x400, v1
	v_sub_u32_e32 v0, v0, v2
	v_lshrrev_b32_e32 v2, 4, v0
	v_bitop3_b32 v0, v2, v0, 32 bitop3:0x6c
	v_ashrrev_i32_e32 v3, 31, v0
	v_lshrrev_b32_e32 v3, 26, v3
	v_lshlrev_b32_e32 v2, 3, v1
	v_add_u32_e32 v3, v0, v3
	v_and_b32_e32 v2, -16, v2
	v_ashrrev_i32_e32 v4, 6, v3
	s_ashr_i32 s5, s4, 6
	v_add_u32_e32 v2, v4, v2
	v_and_b32_e32 v4, 3, v4
	s_ashr_i32 s37, s36, 31
	v_and_or_b32 v4, v2, s6, v4
	s_ashr_i32 s6, s4, 8
	s_lshl_b64 s[14:15], s[36:37], 8
	s_lshl_b64 s[22:23], s[36:37], 9
	s_lshl_b32 s87, s5, 10
	s_add_u32 s88, s62, 0xec00000
	s_addc_u32 s89, s63, 0
	s_ashr_i32 s24, s18, 31
	s_mul_i32 s24, s22, s24
	s_mul_hi_u32 s25, s22, s18
	s_add_i32 s26, s25, s24
	s_lshr_b64 s[24:25], s[36:37], 23
	s_mul_i32 s25, s24, s18
	s_add_i32 s26, s26, s25
	s_ashr_i32 s25, s7, 31
	s_mul_i32 s25, s22, s25
	s_mul_hi_u32 s28, s22, s7
	v_lshlrev_b32_e32 v1, 5, v1
	s_add_i32 s25, s28, s25
	s_mul_i32 s24, s24, s7
	v_and_b32_e32 v15, 32, v1
	v_and_b32_e32 v1, 0xc0, v3
	s_add_i32 s25, s25, s24
	s_mul_i32 s24, s22, s7
	v_sub_u32_e32 v0, v0, v1
	v_lshlrev_b32_e32 v1, 1, v2
	v_lshrrev_b32_e32 v3, 2, v2
	s_add_u32 s28, s12, s24
	v_ashrrev_i16_sdwa v0, v6, sext(v0) dst_sel:DWORD dst_unused:UNUSED_PAD src0_sel:DWORD src1_sel:BYTE_0
	v_and_b32_e32 v1, 24, v1
	v_and_b32_e32 v3, 4, v3
	s_addc_u32 s29, s13, s25
	s_add_i32 s90, s87, 0
	v_bfe_i32 v16, v0, 0, 16
	v_or3_b32 v1, v4, v3, v1
	s_add_i32 m0, s90, 0x10000
	v_add_u32_e32 v0, v15, v16
	v_mul_lo_u32 v1, s36, v1
	global_load_lds_dwordx4 v150, s[28:29]
	s_add_i32 m0, s90, 0x12000
	v_add_lshl_u32 v154, v1, v0, 1
	s_add_u32 s24, s28, s14
	global_load_lds_dwordx4 v154, s[28:29]
	s_addc_u32 s25, s29, s15
	s_add_i32 m0, s90, 0x14000
	s_mul_i32 s27, s22, s18
	global_load_lds_dwordx4 v150, s[24:25]
	s_add_i32 m0, s90, 0x16000
	s_add_u32 s42, s88, s27
	v_mov_b32_e32 v151, v129
	v_mov_b32_e32 v155, v129
	s_addc_u32 s43, s89, s26
	s_add_i32 s91, s90, 0x2000
	v_mul_lo_u32 v17, s36, v2
	v_lshl_add_u64 v[4:5], s[24:25], 0, v[150:151]
	v_lshl_add_u64 v[6:7], s[24:25], 0, v[154:155]
	global_load_lds_dwordx4 v154, s[24:25]
	s_mov_b32 m0, s90
	s_add_u32 s24, s42, s14
	v_add_lshl_u32 v152, v17, v0, 1
	global_load_lds_dwordx4 v148, s[42:43]
	s_mov_b32 m0, s91
	s_addc_u32 s25, s43, s15
	s_add_i32 s92, s90, 0x4000
	global_load_lds_dwordx4 v152, s[42:43]
	s_mov_b32 m0, s92
	s_add_i32 s93, s90, 0x6000
	global_load_lds_dwordx4 v148, s[24:25]
	s_mov_b32 m0, s93
	v_writelane_b32 v255, s94, 30
	global_load_lds_dwordx4 v152, s[24:25]
	v_mov_b32_e32 v149, v129
	v_mov_b32_e32 v153, v129
	s_cmp_eq_u32 s6, 1
	v_writelane_b32 v255, s95, 31
	v_lshl_add_u64 v[0:1], s[28:29], 0, v[150:151]
	v_lshl_add_u64 v[2:3], s[28:29], 0, v[154:155]
	v_lshl_add_u64 v[8:9], s[42:43], 0, v[148:149]
	v_lshl_add_u64 v[10:11], s[42:43], 0, v[152:153]
	s_cselect_b64 s[24:25], -1, 0
	s_and_b32 s94, s5, 3
	s_lshr_b32 s5, s37, 26
	s_add_i32 s5, s36, s5
	s_ashr_i32 s95, s5, 6
	s_lshl_b32 s96, s6, 6
	s_lshl_b32 s5, s6, 13
	s_lshl_b32 s33, s94, 12
	s_add_u32 s26, s60, 0x28580000
	s_addc_u32 s27, s61, 0
	s_add_i32 m0, s90, 0x18000
	v_lshl_add_u64 v[0:1], v[0:1], 0, s[34:35]
	global_load_lds_dwordx4 v[0:1], off
	v_lshl_add_u64 v[0:1], v[2:3], 0, s[34:35]
	s_add_i32 m0, s90, 0x1a000
	s_add_i32 s97, s90, 0x8000
	global_load_lds_dwordx4 v[0:1], off
	v_lshl_add_u64 v[0:1], v[8:9], 0, s[34:35]
	s_mov_b32 m0, s97
	s_add_i32 s48, s90, 0xa000
	global_load_lds_dwordx4 v[0:1], off
	v_lshl_add_u64 v[0:1], v[10:11], 0, s[34:35]
	s_mov_b32 m0, s48
	s_mov_b32 s52, 0
	global_load_lds_dwordx4 v[0:1], off
	s_add_i32 m0, s90, 0x1c000
	v_lshl_add_u64 v[0:1], v[4:5], 0, s[34:35]
	global_load_lds_dwordx4 v[0:1], off
	v_lshl_add_u64 v[0:1], v[6:7], 0, s[34:35]
	s_add_i32 m0, s90, 0x1e000
	s_cmp_gt_i32 s36, 63
	global_load_lds_dwordx4 v[0:1], off
	s_cselect_b64 s[36:37], -1, 0
	s_cmp_lg_u32 s6, 1
	s_cbranch_scc1 .Lpro_0
	s_barrier
.Lpro_0:
	s_waitcnt vmcnt(8)
	s_barrier
	s_add_i32 s49, s95, -2
	v_lshrrev_b32_e32 v0, 1, v157
	s_cmpk_lt_u32 s4, 0x100
	v_and_b32_e32 v156, 24, v0
	s_cselect_b64 s[44:45], -1, 0
	s_lshl_b32 s4, s6, 8
	v_lshlrev_b32_e32 v0, 1, v156
	s_add_i32 s4, s4, 0
	v_lshl_or_b32 v0, v180, 6, v0
	v_and_b32_e32 v1, 32, v146
	s_add_i32 s4, s4, 0x20800
	v_bitop3_b32 v2, v0, s5, v1 bitop3:0xde
	v_bitop3_b32 v181, s33, v0, v1 bitop3:0xf6
	s_add_u32 s46, s60, 0x2c680000
	v_add_u32_e32 v0, v14, v12
	s_waitcnt vmcnt(6)
	s_addc_u32 s47, s61, 0
	v_add_lshl_u32 v128, v0, v13, 1
	v_add_u32_e32 v0, v17, v15
	s_add_u32 s50, s60, 0x2a580000
	v_lshl_add_u64 v[158:159], s[14:15], 0, v[128:129]
	v_add_lshl_u32 v128, v0, v16, 1
	v_add_u32_e32 v182, s4, v146
	s_addc_u32 s51, s61, 0
	v_lshl_add_u64 v[160:161], s[14:15], 0, v[128:129]
	v_add_u32_e32 v183, 0, v2
	v_lshlrev_b32_e32 v184, 2, v156
	s_barrier
	s_branch .LBB0_285

.LBB0_454:
	s_ashr_i32 s22, s6, 2
	s_lshl_b32 s10, s22, 6
	s_lshl_b32 s12, s22, 5
	s_and_b32 s7, s10, 0xffffff00
	s_and_b32 s12, s12, 64
	s_or_b32 s7, s12, s7
	v_or_b32_e32 v0, s7, v72
	s_or_b32 s12, s22, 1
	v_ashrrev_i32_e32 v1, 31, v0
	s_lshl_b32 s7, s12, 6
	s_lshl_b32 s12, s12, 5
	v_lshlrev_b64 v[16:17], 11, v[0:1]
	v_or_b32_e32 v0, 0x80, v0
	s_and_b32 s13, s7, 0xffffff00
	s_and_b32 s12, s12, 0x60
	v_ashrrev_i32_e32 v1, 31, v0
	s_or_b32 s12, s12, s13
	s_and_b32 s11, s5, 0xe0
	v_lshlrev_b64 v[18:19], 11, v[0:1]
	v_or_b32_e32 v0, s12, v72
	v_ashrrev_i32_e32 v1, 31, v0
	v_add_u32_e32 v68, s11, v73
	v_lshlrev_b64 v[20:21], 11, v[0:1]
	v_or_b32_e32 v0, 0x80, v0
	v_add_u32_e32 v70, 0x8000, v68
	v_ashrrev_i32_e32 v1, 31, v0
	v_ashrrev_i32_e32 v71, 31, v70
	v_lshlrev_b64 v[22:23], 11, v[0:1]
	v_lshlrev_b64 v[0:1], 6, v[70:71]
	v_lshl_add_u64 v[12:13], s[0:1], 0, v[0:1]
	global_load_dwordx4 v[32:35], v[12:13], off offset:32
	global_load_dwordx4 v[36:39], v[12:13], off offset:48
	global_load_dwordx4 v[40:43], v[12:13], off
	s_nop 0
	global_load_dwordx4 v[44:47], v[12:13], off offset:16
	v_or_b32_e32 v24, s11, v72
	v_lshlrev_b32_e32 v128, 11, v24
	v_lshl_add_u64 v[138:139], v[64:65], 0, v[128:129]
	v_lshl_add_u64 v[140:141], v[66:67], 0, v[16:17]
	v_lshl_add_u64 v[142:143], v[66:67], 0, v[18:19]
	v_lshl_add_u64 v[148:149], v[66:67], 0, v[20:21]
	v_lshl_add_u64 v[156:157], v[66:67], 0, v[22:23]
	global_load_dwordx4 v[16:19], v[138:139], off
	global_load_dwordx4 v[0:3], v[140:141], off
	global_load_dwordx4 v[4:7], v[142:143], off
	global_load_dwordx4 v[8:11], v[148:149], off
	global_load_dwordx4 v[20:23], v[156:157], off
	global_load_dwordx4 v[76:79], v[138:139], off offset:32
	global_load_dwordx4 v[80:83], v[140:141], off offset:32
	global_load_dwordx4 v[84:87], v[142:143], off offset:32
	global_load_dwordx4 v[88:91], v[148:149], off offset:32
	global_load_dwordx4 v[92:95], v[156:157], off offset:32
	global_load_dwordx4 v[96:99], v[138:139], off offset:64
	global_load_dwordx4 v[100:103], v[140:141], off offset:64
	global_load_dwordx4 v[104:107], v[142:143], off offset:64
	global_load_dwordx4 v[108:111], v[148:149], off offset:64
	global_load_dwordx4 v[112:115], v[156:157], off offset:64
	global_load_dwordx4 v[116:119], v[138:139], off offset:96
	global_load_dwordx4 v[120:123], v[140:141], off offset:96
	global_load_dwordx4 v[124:127], v[142:143], off offset:96
	global_load_dwordx4 v[130:133], v[148:149], off offset:96
	global_load_dwordx4 v[134:137], v[156:157], off offset:96
	s_waitcnt vmcnt(20)
	v_pk_add_f32 v[34:35], v[34:35], v[38:39]
	v_pk_add_f32 v[32:33], v[32:33], v[36:37]
	v_pk_add_f32 v[42:43], v[42:43], v[46:47]
	v_pk_add_f32 v[40:41], v[40:41], v[44:45]
	v_pk_add_f32 v[34:35], v[42:43], v[34:35]
	v_pk_add_f32 v[32:33], v[40:41], v[32:33]
	s_nop 0
	v_pk_mov_b32 v[36:37], v[32:33], v[34:35] op_sel:[1,0]
	v_mov_b32_e32 v33, v35
	v_pk_add_f32 v[32:33], v[36:37], v[32:33]
	s_nop 0
	v_add_f32_e32 v32, v32, v33
	v_fmamk_f32 v32, v32, 0x3a800000, v242
	v_cmp_gt_f32_e32 vcc, s19, v32
	v_mul_f32_e32 v33, 0x4f800000, v32
	s_nop 0
	v_cndmask_b32_e32 v32, v32, v33, vcc
	v_sqrt_f32_e32 v33, v32
	s_nop 0
	v_add_u32_e32 v34, -1, v33
	v_fma_f32 v35, -v34, v33, v32
	v_cmp_ge_f32_e64 s[38:39], 0, v35
	v_add_u32_e32 v35, 1, v33
	s_nop 0
	v_cndmask_b32_e64 v34, v33, v34, s[38:39]
	v_fma_f32 v33, -v35, v33, v32
	v_cmp_lt_f32_e64 s[38:39], 0, v33
	s_nop 1
	v_cndmask_b32_e64 v33, v34, v35, s[38:39]
	v_mul_f32_e32 v34, 0x37800000, v33
	v_cndmask_b32_e32 v33, v33, v34, vcc
	v_cmp_class_f32_e32 vcc, v32, v243
	s_nop 1
	v_cndmask_b32_e32 v69, v33, v32, vcc
	s_waitcnt vmcnt(0)
	v_mfma_f32_32x32x16_bf16 v[32:47], v[16:19], v[0:3], 0
	v_mfma_f32_32x32x16_bf16 v[48:63], v[16:19], v[4:7], 0
	v_mfma_f32_32x32x16_bf16 v[0:15], v[16:19], v[8:11], 0
	v_mfma_f32_32x32x16_bf16 v[16:31], v[16:19], v[20:23], 0
	v_mfma_f32_32x32x16_bf16 v[32:47], v[76:79], v[80:83], v[32:47]
	v_mfma_f32_32x32x16_bf16 v[48:63], v[76:79], v[84:87], v[48:63]
	v_mfma_f32_32x32x16_bf16 v[0:15], v[76:79], v[88:91], v[0:15]
	v_mfma_f32_32x32x16_bf16 v[16:31], v[76:79], v[92:95], v[16:31]
	v_mfma_f32_32x32x16_bf16 v[32:47], v[96:99], v[100:103], v[32:47]
	v_mfma_f32_32x32x16_bf16 v[48:63], v[96:99], v[104:107], v[48:63]
	v_mfma_f32_32x32x16_bf16 v[0:15], v[96:99], v[108:111], v[0:15]
	v_mfma_f32_32x32x16_bf16 v[16:31], v[96:99], v[112:115], v[16:31]
	v_mfma_f32_32x32x16_bf16 v[32:47], v[116:119], v[120:123], v[32:47]
	v_mfma_f32_32x32x16_bf16 v[48:63], v[116:119], v[124:127], v[48:63]
	v_mfma_f32_32x32x16_bf16 v[0:15], v[116:119], v[130:133], v[0:15]
	v_mfma_f32_32x32x16_bf16 v[16:31], v[116:119], v[134:137], v[16:31]
	global_load_dwordx4 v[76:79], v[138:139], off offset:128
	global_load_dwordx4 v[80:83], v[138:139], off offset:160
	global_load_dwordx4 v[84:87], v[140:141], off offset:128
	global_load_dwordx4 v[88:91], v[140:141], off offset:160
	global_load_dwordx4 v[92:95], v[142:143], off offset:128
	global_load_dwordx4 v[96:99], v[142:143], off offset:160
	global_load_dwordx4 v[100:103], v[148:149], off offset:128
	global_load_dwordx4 v[104:107], v[148:149], off offset:160
	global_load_dwordx4 v[108:111], v[156:157], off offset:128
	global_load_dwordx4 v[112:115], v[156:157], off offset:160
	global_load_dwordx4 v[116:119], v[138:139], off offset:192
	global_load_dwordx4 v[120:123], v[138:139], off offset:224
	global_load_dwordx4 v[124:127], v[140:141], off offset:192
	global_load_dwordx4 v[130:133], v[140:141], off offset:224
	global_load_dwordx4 v[134:137], v[142:143], off offset:192
	s_nop 0
	global_load_dwordx4 v[138:141], v[142:143], off offset:224
	s_nop 0
	global_load_dwordx4 v[142:145], v[148:149], off offset:192
	s_nop 0
	global_load_dwordx4 v[148:151], v[148:149], off offset:224
	s_nop 0
	global_load_dwordx4 v[152:155], v[156:157], off offset:192
	s_nop 0
	global_load_dwordx4 v[156:159], v[156:157], off offset:224
	s_waitcnt vmcnt(0)
	v_mfma_f32_32x32x16_bf16 v[32:47], v[76:79], v[84:87], v[32:47]
	v_mfma_f32_32x32x16_bf16 v[48:63], v[76:79], v[92:95], v[48:63]
	v_mfma_f32_32x32x16_bf16 v[0:15], v[76:79], v[100:103], v[0:15]
	v_mfma_f32_32x32x16_bf16 v[16:31], v[76:79], v[108:111], v[16:31]
	v_mfma_f32_32x32x16_bf16 v[32:47], v[80:83], v[88:91], v[32:47]
	v_mfma_f32_32x32x16_bf16 v[48:63], v[80:83], v[96:99], v[48:63]
	v_mfma_f32_32x32x16_bf16 v[0:15], v[80:83], v[104:107], v[0:15]
	v_mfma_f32_32x32x16_bf16 v[16:31], v[80:83], v[112:115], v[16:31]
	v_mfma_f32_32x32x16_bf16 v[32:47], v[116:119], v[124:127], v[32:47]
	v_mfma_f32_32x32x16_bf16 v[48:63], v[116:119], v[134:137], v[48:63]
	v_mfma_f32_32x32x16_bf16 v[0:15], v[116:119], v[142:145], v[0:15]
	v_mfma_f32_32x32x16_bf16 v[16:31], v[116:119], v[152:155], v[16:31]
	v_mfma_f32_32x32x16_bf16 v[32:47], v[120:123], v[130:133], v[32:47]
	v_mfma_f32_32x32x16_bf16 v[48:63], v[120:123], v[138:141], v[48:63]
	v_mfma_f32_32x32x16_bf16 v[0:15], v[120:123], v[148:151], v[0:15]
	v_mfma_f32_32x32x16_bf16 v[16:31], v[120:123], v[156:159], v[16:31]
	s_nop 9
	ds_write2_b32 v74, v32, v48 offset1:32
	ds_write2_b32 v74, v33, v49 offset0:65 offset1:97
	ds_write2_b32 v74, v34, v50 offset0:130 offset1:162
	ds_write2_b32 v74, v35, v51 offset0:195 offset1:227
	v_add_u32_e32 v48, 0x800, v74
	v_add_u32_e32 v49, 0x1000, v74
	ds_write2_b32 v48, v36, v52 offset0:8 offset1:40
	ds_write2_b32 v48, v37, v53 offset0:73 offset1:105
	ds_write2_b32 v48, v38, v54 offset0:138 offset1:170
	ds_write2_b32 v48, v39, v55 offset0:203 offset1:235
	ds_write2_b32 v49, v40, v56 offset0:16 offset1:48
	ds_write2_b32 v49, v41, v57 offset0:81 offset1:113
	ds_write2_b32 v49, v42, v58 offset0:146 offset1:178
	ds_write2_b32 v49, v43, v59 offset0:211 offset1:243
	v_add_u32_e32 v43, 0x1800, v74
	ds_write2_b32 v43, v44, v60 offset0:24 offset1:56
	ds_write2_b32 v43, v45, v61 offset0:89 offset1:121
	ds_write2_b32 v43, v46, v62 offset0:154 offset1:186
	ds_write2_b32 v43, v47, v63 offset0:219 offset1:251
	s_waitcnt lgkmcnt(0)
	s_barrier
	v_add_u32_e32 v37, 0x2080, v75
	v_add_u32_e32 v45, 0x2088, v75
	ds_read2_b32 v[32:33], v75 offset0:2 offset1:3
	ds_read2_b32 v[34:35], v45 offset1:1
	ds_read2_b32 v[38:39], v37 offset1:1
	ds_read2_b32 v[40:41], v75 offset1:1
	v_div_scale_f32 v76, s[12:13], v69, v69, 1.0
	v_rcp_f32_e32 v77, v76
	s_waitcnt lgkmcnt(0)
	v_mov_b32_e32 v47, v32
	v_mov_b32_e32 v46, v40
	v_pk_add_f32 v[52:53], v[46:47], 0 op_sel_hi:[1,0]
	v_add_u32_e32 v46, 0x4108, v75
	v_fma_f32 v79, -v76, v77, 1.0
	v_mov_b32_e32 v32, v41
	v_add_u32_e32 v41, 0x4100, v75
	v_add_u32_e32 v47, 0x6180, v75
	v_add_u32_e32 v50, 0x6188, v75
	ds_read2_b32 v[56:57], v46 offset1:1
	ds_read2_b32 v[58:59], v50 offset1:1
	ds_read2_b32 v[60:61], v47 offset1:1
	ds_read2_b32 v[62:63], v41 offset1:1
	v_div_scale_f32 v78, vcc, 1.0, v69, 1.0
	v_fmac_f32_e32 v77, v79, v77
	v_mul_f32_e32 v79, v78, v77
	v_fma_f32 v80, -v76, v79, v78
	v_fmac_f32_e32 v79, v80, v77
	v_pk_add_f32 v[32:33], v[32:33], 0 op_sel_hi:[1,0]
	v_mov_b32_e32 v54, v38
	v_mov_b32_e32 v55, v34
	v_mov_b32_e32 v34, v39
	v_fma_f32 v76, -v76, v79, v78
	v_pk_add_f32 v[52:53], v[52:53], v[54:55]
	v_pk_add_f32 v[32:33], v[32:33], v[34:35]
	s_waitcnt lgkmcnt(0)
	v_mov_b32_e32 v34, v62
	v_mov_b32_e32 v35, v56
	v_mov_b32_e32 v56, v63
	v_add_u32_e32 v51, 0x8208, v75
	v_div_fmas_f32 v36, v76, v77, v79
	v_pk_add_f32 v[34:35], v[52:53], v[34:35]
	v_pk_add_f32 v[32:33], v[32:33], v[56:57]
	v_add_u32_e32 v42, 0x8200, v75
	v_add_u32_e32 v52, 0xa280, v75
	v_add_u32_e32 v53, 0xa288, v75
	ds_read2_b32 v[54:55], v51 offset1:1
	ds_read2_b32 v[62:63], v53 offset1:1
	ds_read2_b32 v[56:57], v52 offset1:1
	ds_read2_b32 v[76:77], v42 offset1:1
	v_mov_b32_e32 v38, v60
	v_mov_b32_e32 v39, v58
	v_mov_b32_e32 v58, v61
	v_pk_add_f32 v[34:35], v[34:35], v[38:39]
	v_pk_add_f32 v[32:33], v[32:33], v[58:59]
	s_waitcnt lgkmcnt(3)
	v_mov_b32_e32 v39, v54
	s_waitcnt lgkmcnt(0)
	v_mov_b32_e32 v54, v77
	v_mov_b32_e32 v38, v76
	v_pk_add_f32 v[32:33], v[32:33], v[54:55]
	v_add_u32_e32 v54, 0xc308, v75
	v_pk_add_f32 v[34:35], v[34:35], v[38:39]
	v_mov_b32_e32 v38, v56
	v_add_u32_e32 v44, 0xc300, v75
	v_add_u32_e32 v55, 0xe380, v75
	v_add_u32_e32 v56, 0xe388, v75
	ds_read2_b32 v[58:59], v54 offset1:1
	ds_read2_b32 v[60:61], v56 offset1:1
	ds_read2_b32 v[76:77], v55 offset1:1
	ds_read2_b32 v[78:79], v44 offset1:1
	v_mov_b32_e32 v39, v62
	v_mov_b32_e32 v62, v57
	v_pk_add_f32 v[34:35], v[34:35], v[38:39]
	v_pk_add_f32 v[32:33], v[32:33], v[62:63]
	s_waitcnt lgkmcnt(0)
	v_mov_b32_e32 v38, v78
	v_mov_b32_e32 v39, v58
	v_mov_b32_e32 v58, v79
	s_ashr_i32 s18, s6, 6
	v_pk_add_f32 v[34:35], v[34:35], v[38:39]
	v_pk_add_f32 v[32:33], v[32:33], v[58:59]
	v_mov_b32_e32 v38, v76
	v_mov_b32_e32 v39, v60
	v_mov_b32_e32 v60, v77
	s_waitcnt lgkmcnt(0)
	s_barrier
	v_div_fixup_f32 v36, v36, v69, 1.0
	v_pk_add_f32 v[34:35], v[34:35], v[38:39]
	v_pk_add_f32 v[32:33], v[32:33], v[60:61]
	s_cmp_lt_i32 s18, 2
	v_pk_mul_f32 v[38:39], v[36:37], v[34:35] op_sel_hi:[0,1]
	v_pk_mul_f32 v[34:35], v[36:37], v[32:33] op_sel_hi:[0,1]
	s_cselect_b64 s[12:13], -1, 0
	s_cmp_gt_i32 s18, 1
	v_lshlrev_b32_e32 v40, 2, v146
	s_cbranch_scc1 .LBB0_456
	v_pk_mul_f32 v[32:33], v[34:35], v[34:35]
	s_cmp_lt_u32 s22, 16
	v_pk_fma_f32 v[32:33], v[38:39], v[38:39], v[32:33]
	s_nop 0
	v_add_f32_e32 v32, v32, v33
	ds_swizzle_b32 v33, v32 offset:swizzle(SWAP,1)
	s_waitcnt lgkmcnt(0)
	v_add_f32_e32 v32, v32, v33
	ds_swizzle_b32 v33, v32 offset:swizzle(SWAP,2)
	s_waitcnt lgkmcnt(0)
	v_add_f32_e32 v32, v32, v33
	ds_swizzle_b32 v33, v32 offset:swizzle(SWAP,4)
	s_waitcnt lgkmcnt(0)
	v_add_f32_e32 v32, v32, v33
	ds_swizzle_b32 v33, v32 offset:swizzle(SWAP,8)
	s_waitcnt lgkmcnt(0)
	v_add_f32_e32 v32, v32, v33
	v_fmamk_f32 v32, v32, 0x3c800000, v242
	v_cmp_gt_f32_e32 vcc, s19, v32
	v_mul_f32_e32 v33, 0x4f800000, v32
	s_nop 0
	v_cndmask_b32_e32 v32, v32, v33, vcc
	v_sqrt_f32_e32 v33, v32
	s_nop 0
	v_add_u32_e32 v57, -1, v33
	v_fma_f32 v58, -v57, v33, v32
	v_cmp_ge_f32_e64 s[38:39], 0, v58
	v_add_u32_e32 v58, 1, v33
	s_nop 0
	v_cndmask_b32_e64 v57, v33, v57, s[38:39]
	v_fma_f32 v33, -v58, v33, v32
	v_cmp_lt_f32_e64 s[38:39], 0, v33
	s_nop 1
	v_cndmask_b32_e64 v33, v57, v58, s[38:39]
	v_mul_f32_e32 v57, 0x37800000, v33
	v_cndmask_b32_e32 v33, v33, v57, vcc
	v_cmp_class_f32_e32 vcc, v32, v243
	s_nop 1
	v_cndmask_b32_e32 v32, v33, v32, vcc
	v_div_scale_f32 v33, s[14:15], v32, v32, 1.0
	v_rcp_f32_e32 v57, v33
	s_cselect_b32 s15, s57, s59
	s_cselect_b32 s14, s56, s58
	v_fma_f32 v58, -v33, v57, 1.0
	v_fmac_f32_e32 v57, v58, v57
	v_div_scale_f32 v58, vcc, 1.0, v32, 1.0
	v_mul_f32_e32 v59, v58, v57
	v_fma_f32 v60, -v33, v59, v58
	v_fmac_f32_e32 v59, v60, v57
	v_fma_f32 v33, -v33, v59, v58
	v_div_fmas_f32 v33, v33, v57, v59
	global_load_dwordx4 v[58:61], v40, s[14:15]
	v_div_fixup_f32 v62, v33, v32, 1.0
	s_waitcnt vmcnt(0)
	v_pk_mul_f32 v[32:33], v[58:59], v[62:63] op_sel_hi:[1,0]
	v_mov_b32_e32 v58, v38
	v_mov_b32_e32 v59, v34
	v_pk_mul_f32 v[32:33], v[58:59], v[32:33]
	v_pk_mul_f32 v[58:59], v[60:61], v[62:63] op_sel_hi:[1,0]
	v_mov_b32_e32 v34, v39
	v_pk_mul_f32 v[34:35], v[34:35], v[58:59]
	s_branch .LBB0_457

.LBB0_746:
	s_load_dwordx2 s[12:13], s[2:3], 0x118
	v_and_b32_e32 v147, 15, v146
	v_lshlrev_b32_e32 v144, 2, v147
	s_waitcnt lgkmcnt(0)
	s_add_u32 s2, s12, 0xec00000
	s_addc_u32 s3, s13, 0
	s_add_u32 s10, s12, 0x210000
	s_addc_u32 s11, s13, 0
	s_add_u32 s14, s12, 0x2900000
	s_addc_u32 s15, s13, 0
	s_andn2_b64 vcc, exec, s[22:23]
	s_cbranch_vccnz .LBB0_788
	v_bfe_i32 v2, v145, 27, 1
	v_lshlrev_b32_e32 v0, 4, v145
	v_lshrrev_b32_e32 v2, 22, v2
	v_add_u32_e32 v2, v0, v2
	v_and_b32_e32 v2, 0xfffffc00, v2
	v_sub_u32_e32 v2, v0, v2
	v_ashrrev_i32_e32 v1, 31, v145
	v_lshrrev_b32_e32 v3, 4, v2
	v_lshrrev_b32_e32 v1, 26, v1
	v_bitop3_b32 v2, v3, v2, 32 bitop3:0x6c
	v_add_u32_e32 v1, v145, v1
	v_ashrrev_i32_e32 v4, 31, v2
	v_ashrrev_i32_e32 v1, 6, v1
	v_lshrrev_b32_e32 v4, 26, v4
	v_lshlrev_b32_e32 v3, 3, v1
	v_add_u32_e32 v4, v2, v4
	v_and_b32_e32 v3, -16, v3
	v_ashrrev_i32_e32 v5, 6, v4
	v_lshlrev_b32_e32 v1, 5, v1
	v_add_u32_e32 v3, v5, v3
	v_and_b32_e32 v12, 32, v1
	v_and_b32_e32 v1, 0xc0, v4
	v_sub_u32_e32 v1, v2, v1
	v_mov_b32_e32 v6, 1
	v_lshlrev_b32_e32 v2, 1, v3
	v_lshrrev_b32_e32 v4, 2, v3
	v_and_b32_e32 v5, 3, v5
	s_mov_b32 s18, 0x7fffffe0
	v_ashrrev_i16_sdwa v1, v6, sext(v1) dst_sel:DWORD dst_unused:UNUSED_PAD src0_sel:DWORD src1_sel:BYTE_0
	v_and_b32_e32 v2, 24, v2
	v_and_b32_e32 v4, 4, v4
	v_and_or_b32 v5, v3, s18, v5
	v_bfe_i32 v13, v1, 0, 16
	v_or3_b32 v2, v5, v4, v2
	v_add_u32_e32 v1, v12, v13
	v_mul_lo_u32 v14, v3, s36
	v_mul_lo_u32 v2, v2, s36
	v_add_u32_e32 v0, 0x2000, v0
	v_add_lshl_u32 v130, v1, v14, 1
	v_add_lshl_u32 v132, v2, v1, 1
	v_ashrrev_i32_e32 v1, 31, v0
	v_lshrrev_b32_e32 v1, 22, v1
	v_add_u32_e32 v1, v0, v1
	v_ashrrev_i32_e32 v1, 10, v1
	s_add_u32 s6, s12, 0x1ee00000
	v_mul_i32_i24_e32 v2, 0x400, v1
	s_addc_u32 s7, s13, 0
	v_sub_u32_e32 v0, v0, v2
	s_ashr_i32 s37, s36, 31
	v_lshrrev_b32_e32 v2, 4, v0
	s_lshl_b64 s[24:25], s[36:37], 9
	s_ashr_i32 s20, s70, 31
	v_bitop3_b32 v0, v2, v0, 32 bitop3:0x6c
	s_mul_i32 s20, s24, s20
	s_mul_hi_u32 s26, s24, s70
	v_ashrrev_i32_e32 v3, 31, v0
	s_add_i32 s20, s26, s20
	s_lshr_b64 s[26:27], s[36:37], 23
	v_lshrrev_b32_e32 v3, 26, v3
	s_mul_i32 s27, s26, s70
	v_lshlrev_b32_e32 v2, 3, v1
	v_add_u32_e32 v3, v0, v3
	s_add_i32 s40, s20, s27
	s_ashr_i32 s20, s64, 31
	v_and_b32_e32 v2, -16, v2
	v_ashrrev_i32_e32 v4, 6, v3
	s_mul_i32 s20, s24, s20
	s_mul_hi_u32 s27, s24, s64
	s_ashr_i32 s38, s33, 6
	v_add_u32_e32 v2, v4, v2
	v_lshlrev_b32_e32 v1, 5, v1
	v_and_b32_e32 v4, 3, v4
	s_add_i32 s20, s27, s20
	s_mul_i32 s26, s26, s64
	v_and_b32_e32 v15, 32, v1
	v_and_b32_e32 v1, 0xc0, v3
	v_and_or_b32 v4, v2, s18, v4
	s_ashr_i32 s39, s33, 8
	s_lshl_b64 s[22:23], s[36:37], 8
	s_lshl_b32 s18, s38, 10
	s_add_i32 s20, s20, s26
	s_mul_i32 s26, s24, s64
	v_sub_u32_e32 v0, v0, v1
	v_lshlrev_b32_e32 v1, 1, v2
	v_lshrrev_b32_e32 v3, 2, v2
	s_add_u32 s28, s14, s26
	v_ashrrev_i16_sdwa v0, v6, sext(v0) dst_sel:DWORD dst_unused:UNUSED_PAD src0_sel:DWORD src1_sel:BYTE_0
	v_and_b32_e32 v1, 24, v1
	v_and_b32_e32 v3, 4, v3
	s_addc_u32 s29, s15, s20
	s_add_i32 s20, s18, 0
	v_bfe_i32 v16, v0, 0, 16
	v_or3_b32 v1, v4, v3, v1
	s_add_i32 m0, s20, 0x10000
	v_add_u32_e32 v0, v15, v16
	v_mul_lo_u32 v1, v1, s36
	global_load_lds_dwordx4 v132, s[28:29]
	s_add_i32 m0, s20, 0x12000
	v_add_lshl_u32 v136, v1, v0, 1
	s_add_u32 s26, s28, s22
	global_load_lds_dwordx4 v136, s[28:29]
	s_addc_u32 s27, s29, s23
	s_add_i32 m0, s20, 0x14000
	s_mul_i32 s41, s24, s70
	global_load_lds_dwordx4 v132, s[26:27]
	s_add_i32 m0, s20, 0x16000
	s_add_u32 s50, s6, s41
	v_mov_b32_e32 v133, v129
	v_mov_b32_e32 v137, v129
	s_addc_u32 s51, s7, s40
	s_add_i32 s48, s20, 0x2000
	v_mul_lo_u32 v17, v2, s36
	v_lshl_add_u64 v[4:5], s[26:27], 0, v[132:133]
	v_lshl_add_u64 v[6:7], s[26:27], 0, v[136:137]
	global_load_lds_dwordx4 v136, s[26:27]
	s_mov_b32 m0, s20
	s_add_u32 s26, s50, s22
	v_add_lshl_u32 v134, v0, v17, 1
	global_load_lds_dwordx4 v130, s[50:51]
	s_mov_b32 m0, s48
	s_addc_u32 s27, s51, s23
	s_add_i32 s49, s20, 0x4000
	global_load_lds_dwordx4 v134, s[50:51]
	s_mov_b32 m0, s49
	s_add_i32 s52, s20, 0x6000
	global_load_lds_dwordx4 v130, s[26:27]
	s_mov_b32 m0, s52
	v_mov_b32_e32 v131, v129
	global_load_lds_dwordx4 v134, s[26:27]
	v_mov_b32_e32 v135, v129
	s_cmp_eq_u32 s39, 1
	v_lshl_add_u64 v[0:1], s[28:29], 0, v[132:133]
	v_lshl_add_u64 v[2:3], s[28:29], 0, v[136:137]
	v_lshl_add_u64 v[8:9], s[50:51], 0, v[130:131]
	v_lshl_add_u64 v[10:11], s[50:51], 0, v[134:135]
	s_cselect_b64 s[26:27], -1, 0
	s_add_i32 m0, s20, 0x18000
	v_lshl_add_u64 v[0:1], v[0:1], 0, s[34:35]
	global_load_lds_dwordx4 v[0:1], off
	v_lshl_add_u64 v[0:1], v[2:3], 0, s[34:35]
	s_add_i32 m0, s20, 0x1a000
	s_add_i32 s53, s20, 0x8000
	global_load_lds_dwordx4 v[0:1], off
	v_lshl_add_u64 v[0:1], v[8:9], 0, s[34:35]
	s_mov_b32 m0, s53
	s_add_i32 s56, s20, 0xa000
	global_load_lds_dwordx4 v[0:1], off
	v_lshl_add_u64 v[0:1], v[10:11], 0, s[34:35]
	s_mov_b32 m0, s56
	s_lshr_b32 s37, s37, 26
	global_load_lds_dwordx4 v[0:1], off
	s_add_i32 m0, s20, 0x1c000
	v_lshl_add_u64 v[0:1], v[4:5], 0, s[34:35]
	global_load_lds_dwordx4 v[0:1], off
	v_lshl_add_u64 v[0:1], v[6:7], 0, s[34:35]
	s_add_i32 m0, s20, 0x1e000
	s_add_i32 s37, s36, s37
	global_load_lds_dwordx4 v[0:1], off
	s_cmp_lg_u32 s39, 1
	s_cbranch_scc1 .Lpro_1
	s_barrier
.Lpro_1:
	s_waitcnt vmcnt(8)
	s_barrier
	v_bfe_u32 v0, v146, 4, 2
	v_lshlrev_b32_e32 v2, 4, v0
	s_and_b32 s40, s38, 3
	s_ashr_i32 s57, s37, 6
	v_lshl_or_b32 v2, v147, 6, v2
	s_lshl_b32 s37, s39, 13
	v_and_b32_e32 v3, 32, v144
	v_bitop3_b32 v4, v2, s37, v3 bitop3:0xde
	s_lshl_b32 s37, s40, 12
	s_cmp_gt_i32 s36, 63
	v_bitop3_b32 v149, s37, v2, v3 bitop3:0xf6
	s_cselect_b64 s[36:37], -1, 0
	s_add_i32 s58, s57, -2
	v_lshl_or_b32 v148, s39, 6, v147
	v_lshlrev_b32_e32 v1, 3, v0
	s_cmpk_lt_u32 s33, 0x100
	v_cmp_eq_u32_e64 s[38:39], 0, v0
	v_add_u32_e32 v0, v14, v12
	s_waitcnt vmcnt(6)
	s_cselect_b64 s[44:45], -1, 0
	s_ashr_i32 s60, s4, 31
	s_ashr_i32 s61, s5, 31
	s_lshl_b32 s33, s40, 2
	v_add_lshl_u32 v128, v0, v13, 1
	v_add_u32_e32 v0, v17, v15
	s_add_u32 s62, s10, s33
	v_lshl_add_u64 v[138:139], s[22:23], 0, v[128:129]
	v_add_lshl_u32 v128, v0, v16, 1
	v_lshl_or_b32 v150, s40, 5, v1
	s_mov_b32 s59, 0
	s_addc_u32 s63, s11, 0
	v_lshl_add_u64 v[140:141], s[22:23], 0, v[128:129]
	v_add_u32_e32 v151, 0, v4
	s_barrier
	s_branch .LBB0_752

.LBB0_881:
	s_add_u32 s14, s58, 0x12c80000
	s_addc_u32 s15, s59, 0
	s_add_u32 s12, s58, 0x16d00000
	s_addc_u32 s13, s59, 0
	s_add_u32 s22, s58, 0x1c00000
	s_addc_u32 s23, s59, 0
	v_and_b32_e32 v180, 15, v179
	s_add_u32 s64, s56, 0x28540000
	v_lshlrev_b32_e32 v157, 2, v180
	s_addc_u32 s65, s57, 0
	s_andn2_b64 vcc, exec, s[0:1]
	s_cbranch_vccnz .LBB0_1021
	s_waitcnt vmcnt(3)
	v_bfe_i32 v2, v178, 27, 1
	v_lshlrev_b32_e32 v0, 4, v178
	v_lshrrev_b32_e32 v2, 22, v2
	v_add_u32_e32 v2, v0, v2
	v_and_b32_e32 v2, 0xfffffc00, v2
	v_sub_u32_e32 v2, v0, v2
	v_ashrrev_i32_e32 v1, 31, v178
	v_lshrrev_b32_e32 v3, 4, v2
	v_lshrrev_b32_e32 v1, 26, v1
	v_bitop3_b32 v2, v3, v2, 32 bitop3:0x6c
	v_add_u32_e32 v1, v178, v1
	s_waitcnt vmcnt(2)
	v_ashrrev_i32_e32 v4, 31, v2
	v_ashrrev_i32_e32 v1, 6, v1
	v_lshrrev_b32_e32 v4, 26, v4
	v_lshlrev_b32_e32 v3, 3, v1
	v_add_u32_e32 v4, v2, v4
	v_and_b32_e32 v3, -16, v3
	v_ashrrev_i32_e32 v5, 6, v4
	v_lshlrev_b32_e32 v1, 5, v1
	v_add_u32_e32 v3, v5, v3
	s_waitcnt vmcnt(0)
	v_and_b32_e32 v12, 32, v1
	v_and_b32_e32 v1, 0xc0, v4
	v_sub_u32_e32 v1, v2, v1
	v_mov_b32_e32 v6, 1
	v_lshlrev_b32_e32 v2, 1, v3
	v_lshrrev_b32_e32 v4, 2, v3
	v_and_b32_e32 v5, 3, v5
	s_mov_b32 s0, 0x7fffffe0
	v_ashrrev_i16_sdwa v1, v6, sext(v1) dst_sel:DWORD dst_unused:UNUSED_PAD src0_sel:DWORD src1_sel:BYTE_0
	v_and_b32_e32 v2, 24, v2
	v_and_b32_e32 v4, 4, v4
	v_and_or_b32 v5, v3, s0, v5
	v_bfe_i32 v13, v1, 0, 16
	v_or3_b32 v2, v5, v4, v2
	v_add_u32_e32 v1, v12, v13
	v_mul_lo_u32 v14, s10, v3
	v_mul_lo_u32 v2, s10, v2
	v_add_u32_e32 v0, 0x2000, v0
	v_add_lshl_u32 v150, v14, v1, 1
	v_add_lshl_u32 v128, v2, v1, 1
	v_ashrrev_i32_e32 v1, 31, v0
	v_lshrrev_b32_e32 v1, 22, v1
	v_add_u32_e32 v1, v0, v1
	v_ashrrev_i32_e32 v1, 10, v1
	v_mul_i32_i24_e32 v2, 0x400, v1
	v_sub_u32_e32 v0, v0, v2
	v_lshrrev_b32_e32 v2, 4, v0
	v_bitop3_b32 v0, v2, v0, 32 bitop3:0x6c
	v_ashrrev_i32_e32 v3, 31, v0
	v_lshrrev_b32_e32 v3, 26, v3
	v_lshlrev_b32_e32 v2, 3, v1
	v_add_u32_e32 v3, v0, v3
	v_and_b32_e32 v2, -16, v2
	v_ashrrev_i32_e32 v4, 6, v3
	v_add_u32_e32 v2, v4, v2
	v_and_b32_e32 v4, 3, v4
	s_ashr_i32 s18, s6, 6
	s_ashr_i32 s11, s10, 31
	s_ashr_i32 s7, s6, 8
	v_and_or_b32 v4, v2, s0, v4
	s_lshl_b64 s[2:3], s[10:11], 8
	s_lshl_b64 s[0:1], s[10:11], 9
	s_lshl_b32 s67, s18, 10
	s_add_u32 s52, s58, 0xec00000
	s_addc_u32 s53, s59, 0
	s_ashr_i32 s24, s4, 31
	s_mul_i32 s24, s0, s24
	s_mul_hi_u32 s25, s0, s4
	s_add_i32 s26, s25, s24
	s_lshr_b64 s[24:25], s[10:11], 23
	s_mul_i32 s25, s24, s4
	s_add_i32 s26, s26, s25
	s_ashr_i32 s25, s5, 31
	s_mul_i32 s25, s0, s25
	s_mul_hi_u32 s28, s0, s5
	v_lshlrev_b32_e32 v1, 5, v1
	s_add_i32 s25, s28, s25
	s_mul_i32 s24, s24, s5
	v_and_b32_e32 v15, 32, v1
	v_and_b32_e32 v1, 0xc0, v3
	s_add_i32 s25, s25, s24
	s_mul_i32 s24, s0, s5
	v_sub_u32_e32 v0, v0, v1
	v_lshlrev_b32_e32 v1, 1, v2
	v_lshrrev_b32_e32 v3, 2, v2
	s_add_u32 s28, s22, s24
	v_ashrrev_i16_sdwa v0, v6, sext(v0) dst_sel:DWORD dst_unused:UNUSED_PAD src0_sel:DWORD src1_sel:BYTE_0
	v_and_b32_e32 v1, 24, v1
	v_and_b32_e32 v3, 4, v3
	s_addc_u32 s29, s23, s25
	s_add_i32 s86, s67, 0
	v_bfe_i32 v16, v0, 0, 16
	v_or3_b32 v1, v4, v3, v1
	s_add_i32 m0, s86, 0x10000
	v_add_u32_e32 v0, v15, v16
	v_mul_lo_u32 v1, s10, v1
	global_load_lds_dwordx4 v128, s[28:29]
	s_add_i32 m0, s86, 0x12000
	v_add_lshl_u32 v154, v1, v0, 1
	s_add_u32 s24, s28, s2
	global_load_lds_dwordx4 v154, s[28:29]
	s_addc_u32 s25, s29, s3
	s_add_i32 m0, s86, 0x14000
	s_mul_i32 s27, s0, s4
	global_load_lds_dwordx4 v128, s[24:25]
	s_add_i32 m0, s86, 0x16000
	s_add_u32 s44, s52, s27
	s_addc_u32 s45, s53, s26
	s_add_i32 s87, s86, 0x2000
	v_mul_lo_u32 v17, s10, v2
	v_mov_b32_e32 v155, v129
	global_load_lds_dwordx4 v154, s[24:25]
	s_mov_b32 m0, s86
	s_add_u32 s26, s44, s2
	v_add_lshl_u32 v152, v17, v0, 1
	v_lshl_add_u64 v[4:5], s[24:25], 0, v[128:129]
	v_lshl_add_u64 v[6:7], s[24:25], 0, v[154:155]
	global_load_lds_dwordx4 v150, s[44:45]
	s_mov_b32 m0, s87
	s_addc_u32 s27, s45, s3
	s_add_i32 s24, s86, 0x4000
	global_load_lds_dwordx4 v152, s[44:45]
	s_mov_b32 m0, s24
	s_add_i32 s25, s86, 0x6000
	global_load_lds_dwordx4 v150, s[26:27]
	s_mov_b32 m0, s25
	s_cmp_eq_u32 s7, 1
	global_load_lds_dwordx4 v152, s[26:27]
	s_cselect_b64 s[26:27], -1, 0
	v_mov_b32_e32 v151, v129
	v_mov_b32_e32 v153, v129
	v_writelane_b32 v255, s26, 32
	v_lshl_add_u64 v[0:1], s[28:29], 0, v[128:129]
	v_lshl_add_u64 v[2:3], s[28:29], 0, v[154:155]
	v_lshl_add_u64 v[8:9], s[44:45], 0, v[150:151]
	v_lshl_add_u64 v[10:11], s[44:45], 0, v[152:153]
	v_writelane_b32 v255, s27, 33
	v_lshrrev_b32_e32 v18, 1, v179
	s_lshr_b32 s11, s11, 26
	v_and_b32_e32 v18, 24, v18
	s_add_i32 s11, s10, s11
	v_lshlrev_b32_e32 v19, 1, v18
	s_ashr_i32 s90, s11, 6
	v_lshl_or_b32 v19, v180, 6, v19
	s_lshl_b32 s11, s7, 13
	v_and_b32_e32 v20, 32, v157
	v_bitop3_b32 v21, v19, s11, v20 bitop3:0xde
	s_lshl_b32 s11, s18, 5
	s_and_b32 s18, s11, 0x60
	s_lshl_b32 s85, s7, 6
	s_lshl_b32 s11, s18, 7
	s_add_u32 s56, s56, 0x28500000
	s_addc_u32 s57, s57, 0
	s_add_i32 m0, s86, 0x18000
	v_lshl_add_u64 v[0:1], v[0:1], 0, s[34:35]
	global_load_lds_dwordx4 v[0:1], off
	v_lshl_add_u64 v[0:1], v[2:3], 0, s[34:35]
	s_add_i32 m0, s86, 0x1a000
	s_add_i32 s88, s86, 0x8000
	global_load_lds_dwordx4 v[0:1], off
	v_lshl_add_u64 v[0:1], v[8:9], 0, s[34:35]
	s_mov_b32 m0, s88
	s_add_i32 s89, s86, 0xa000
	global_load_lds_dwordx4 v[0:1], off
	v_lshl_add_u64 v[0:1], v[10:11], 0, s[34:35]
	s_mov_b32 m0, s89
	v_bitop3_b32 v181, s11, v19, v20 bitop3:0xf6
	global_load_lds_dwordx4 v[0:1], off
	s_add_i32 m0, s86, 0x1c000
	v_lshl_add_u64 v[0:1], v[4:5], 0, s[34:35]
	global_load_lds_dwordx4 v[0:1], off
	v_lshl_add_u64 v[0:1], v[6:7], 0, s[34:35]
	s_add_i32 m0, s86, 0x1e000
	s_cmp_gt_i32 s10, 63
	global_load_lds_dwordx4 v[0:1], off
	s_cselect_b64 s[36:37], -1, 0
	s_cmp_lg_u32 s7, 1
	s_cbranch_scc1 .Lpro_2
	s_barrier
.Lpro_2:
	s_waitcnt vmcnt(8)
	s_barrier
	s_add_i32 s73, s90, -2
	s_cmpk_lt_u32 s6, 0x100
	v_add_u32_e32 v0, v14, v12
	s_cselect_b64 s[10:11], -1, 0
	s_lshl_b32 s6, s7, 8
	v_add_lshl_u32 v0, v0, v13, 1
	v_mov_b32_e32 v1, v129
	s_waitcnt vmcnt(6)
	s_add_i32 s6, s6, 0
	v_lshl_add_u64 v[158:159], s[2:3], 0, v[0:1]
	v_add_u32_e32 v0, v17, v15
	s_add_i32 s6, s6, 0x20800
	v_add_lshl_u32 v0, v0, v16, 1
	v_subrev_co_u32_e64 v156, s[38:39], 13, v180
	v_add_u32_e32 v182, s6, v157
	v_or_b32_e32 v183, s18, v18
	v_lshl_add_u64 v[160:161], s[2:3], 0, v[0:1]
	s_mov_b32 s6, 0
	v_add_u32_e32 v184, 0, v21
	s_barrier
	s_branch .LBB0_887

.LBB0_1147:
	s_load_dwordx2 s[24:25], s[2:3], 0x118
	s_load_dwordx2 s[0:1], s[2:3], 0xb0
	s_nop 0
	s_load_dwordx2 s[2:3], s[2:3], 0xc0
	v_and_b32_e32 v197, 15, v196
	v_lshlrev_b32_e32 v194, 2, v197
	s_waitcnt lgkmcnt(0)
	s_add_u32 s10, s24, 0x1ad80000
	s_addc_u32 s11, s25, 0
	s_add_u32 s12, s24, 0x33080000
	s_addc_u32 s13, s25, 0
	s_add_u32 s14, s24, 0x3b180000
	s_addc_u32 s15, s25, 0
	s_add_u32 s22, s24, 0x200000
	s_addc_u32 s23, s25, 0
	s_add_u32 s26, s24, 0x2000000
	s_addc_u32 s27, s25, 0
	s_andn2_b64 vcc, exec, s[28:29]
	s_cbranch_vccnz .LBB0_1429
	v_bfe_i32 v1, v195, 27, 1
	v_lshlrev_b32_e32 v3, 4, v195
	v_lshrrev_b32_e32 v1, 22, v1
	v_add_u32_e32 v1, v3, v1
	v_and_b32_e32 v1, 0xfffffc00, v1
	v_sub_u32_e32 v1, v3, v1
	v_ashrrev_i32_e32 v0, 31, v195
	v_lshrrev_b32_e32 v2, 4, v1
	v_lshrrev_b32_e32 v0, 26, v0
	v_bitop3_b32 v1, v2, v1, 32 bitop3:0x6c
	v_add_u32_e32 v0, v195, v0
	v_ashrrev_i32_e32 v4, 31, v1
	v_ashrrev_i32_e32 v0, 6, v0
	v_lshrrev_b32_e32 v4, 26, v4
	v_lshlrev_b32_e32 v2, 3, v0
	v_add_u32_e32 v4, v1, v4
	v_and_b32_e32 v2, -16, v2
	v_ashrrev_i32_e32 v5, 6, v4
	v_add_u32_e32 v2, v5, v2
	v_and_b32_e32 v4, 0xc0, v4
	v_sub_u32_e32 v1, v1, v4
	v_mov_b32_e32 v9, 1
	v_lshlrev_b32_e32 v6, 1, v2
	v_lshrrev_b32_e32 v7, 2, v2
	v_and_b32_e32 v5, 3, v5
	s_mov_b32 s18, 0x7fffffe0
	v_lshlrev_b32_e32 v0, 5, v0
	v_ashrrev_i16_sdwa v1, v9, sext(v1) dst_sel:DWORD dst_unused:UNUSED_PAD src0_sel:DWORD src1_sel:BYTE_0
	v_and_b32_e32 v6, 24, v6
	v_and_b32_e32 v7, 4, v7
	v_and_or_b32 v5, v2, s18, v5
	v_and_b32_e32 v0, 32, v0
	v_bfe_i32 v1, v1, 0, 16
	v_or3_b32 v5, v5, v7, v6
	v_add_u32_e32 v4, v0, v1
	v_mul_lo_u32 v2, v2, s38
	v_mul_lo_u32 v5, v5, s38
	v_add_u32_e32 v3, 0x2000, v3
	v_add_lshl_u32 v174, v4, v2, 1
	v_add_lshl_u32 v176, v5, v4, 1
	v_ashrrev_i32_e32 v4, 31, v3
	v_lshrrev_b32_e32 v4, 22, v4
	v_add_u32_e32 v4, v3, v4
	v_ashrrev_i32_e32 v4, 10, v4
	v_mul_i32_i24_e32 v5, 0x400, v4
	v_sub_u32_e32 v3, v3, v5
	s_ashr_i32 s39, s38, 31
	v_lshrrev_b32_e32 v5, 4, v3
	s_lshl_b64 s[42:43], s[38:39], 9
	s_ashr_i32 s28, s6, 31
	v_bitop3_b32 v5, v5, v3, 32 bitop3:0x6c
	s_mul_i32 s28, s42, s28
	s_mul_hi_u32 s29, s42, s6
	v_ashrrev_i32_e32 v6, 31, v5
	s_add_i32 s33, s29, s28
	s_lshr_b64 s[28:29], s[38:39], 23
	v_lshrrev_b32_e32 v6, 26, v6
	s_mul_i32 s29, s28, s6
	v_lshlrev_b32_e32 v3, 3, v4
	v_add_u32_e32 v6, v5, v6
	s_add_i32 s33, s33, s29
	s_ashr_i32 s29, s7, 1
	v_and_b32_e32 v3, -16, v3
	v_ashrrev_i32_e32 v7, 6, v6
	s_mul_hi_i32 s44, s29, 0x1020000
	s_mul_i32 s45, s29, 0x1020000
	s_ashr_i32 s29, s7, 31
	v_add_u32_e32 v8, v7, v3
	v_and_b32_e32 v7, 3, v7
	s_mul_i32 s29, s42, s29
	s_mul_hi_u32 s41, s42, s7
	v_and_or_b32 v7, v8, s18, v7
	s_ashr_i32 s18, s4, 6
	s_add_i32 s29, s41, s29
	s_mul_i32 s28, s28, s7
	s_ashr_i32 s5, s4, 8
	s_lshl_b64 s[36:37], s[38:39], 8
	s_lshl_b32 s61, s18, 10
	s_add_i32 s29, s29, s28
	s_mul_i32 s28, s42, s7
	v_lshlrev_b32_e32 v3, 5, v4
	v_and_b32_e32 v4, 0xc0, v6
	s_add_u32 s28, s26, s28
	v_sub_u32_e32 v4, v5, v4
	s_addc_u32 s29, s27, s29
	s_add_i32 s62, s61, 0
	v_ashrrev_i16_sdwa v4, v9, sext(v4) dst_sel:DWORD dst_unused:UNUSED_PAD src0_sel:DWORD src1_sel:BYTE_0
	v_lshlrev_b32_e32 v5, 1, v8
	v_lshrrev_b32_e32 v9, 2, v8
	s_add_i32 m0, s62, 0x10000
	v_and_b32_e32 v5, 24, v5
	v_and_b32_e32 v9, 4, v9
	s_mul_i32 s40, s42, s6
	global_load_lds_dwordx4 v176, s[28:29]
	s_add_i32 m0, s62, 0x12000
	v_and_b32_e32 v3, 32, v3
	v_bfe_i32 v4, v4, 0, 16
	v_or3_b32 v7, v7, v9, v5
	s_add_u32 s46, s10, s40
	v_add_u32_e32 v6, v3, v4
	v_mul_lo_u32 v7, v7, s38
	s_addc_u32 s33, s11, s33
	v_add_lshl_u32 v180, v7, v6, 1
	s_add_u32 s40, s28, s36
	global_load_lds_dwordx4 v180, s[28:29]
	s_addc_u32 s41, s29, s37
	s_add_i32 m0, s62, 0x14000
	v_mul_lo_u32 v5, v8, s38
	global_load_lds_dwordx4 v176, s[40:41]
	s_add_i32 m0, s62, 0x16000
	s_add_u32 s58, s46, s45
	s_addc_u32 s59, s33, s44
	s_add_i32 s63, s62, 0x2000
	global_load_lds_dwordx4 v180, s[40:41]
	s_mov_b32 m0, s62
	s_add_u32 s44, s58, s36
	v_add_lshl_u32 v178, v6, v5, 1
	global_load_lds_dwordx4 v174, s[58:59]
	s_mov_b32 m0, s63
	s_addc_u32 s45, s59, s37
	s_add_i32 s64, s62, 0x4000
	global_load_lds_dwordx4 v178, s[58:59]
	s_mov_b32 m0, s64
	s_add_i32 s65, s62, 0x6000
	global_load_lds_dwordx4 v174, s[44:45]
	s_mov_b32 m0, s65
	s_cmp_eq_u32 s5, 1
	global_load_lds_dwordx4 v178, s[44:45]
	s_cselect_b64 s[44:45], -1, 0
	v_mov_b32_e32 v177, v129
	v_lshl_add_u64 v[6:7], s[28:29], 0, v[176:177]
	v_mov_b32_e32 v181, v129
	v_lshl_add_u64 v[8:9], s[28:29], 0, v[180:181]
	v_mov_b32_e32 v175, v129
	s_add_i32 m0, s62, 0x18000
	v_lshl_add_u64 v[6:7], v[6:7], 0, s[34:35]
	v_lshl_add_u64 v[14:15], s[58:59], 0, v[174:175]
	v_mov_b32_e32 v179, v129
	global_load_lds_dwordx4 v[6:7], off
	v_lshl_add_u64 v[6:7], v[8:9], 0, s[34:35]
	s_add_i32 m0, s62, 0x1a000
	s_add_i32 s67, s62, 0x8000
	v_lshl_add_u64 v[16:17], s[58:59], 0, v[178:179]
	global_load_lds_dwordx4 v[6:7], off
	v_lshl_add_u64 v[6:7], v[14:15], 0, s[34:35]
	s_mov_b32 m0, s67
	s_add_i32 s48, s62, 0xa000
	v_lshl_add_u64 v[10:11], s[40:41], 0, v[176:177]
	global_load_lds_dwordx4 v[6:7], off
	v_lshl_add_u64 v[6:7], v[16:17], 0, s[34:35]
	s_mov_b32 m0, s48
	v_lshl_add_u64 v[12:13], s[40:41], 0, v[180:181]
	global_load_lds_dwordx4 v[6:7], off
	s_add_i32 m0, s62, 0x1c000
	v_lshl_add_u64 v[6:7], v[10:11], 0, s[34:35]
	global_load_lds_dwordx4 v[6:7], off
	v_lshl_add_u64 v[6:7], v[12:13], 0, s[34:35]
	s_add_i32 m0, s62, 0x1e000
	v_lshl_or_b32 v202, s5, 6, v197
	global_load_lds_dwordx4 v[6:7], off
	s_cmp_lg_u32 s5, 1
	s_cbranch_scc1 .Lpro_3
	s_barrier
.Lpro_3:
	s_waitcnt vmcnt(8)
	s_barrier
	v_lshrrev_b32_e32 v6, 1, v196
	v_and_b32_e32 v6, 24, v6
	v_lshlrev_b32_e32 v7, 1, v6
	v_lshl_or_b32 v7, v197, 6, v7
	s_lshl_b32 s5, s5, 13
	v_and_b32_e32 v8, 32, v194
	s_lshr_b32 s33, s39, 26
	v_bitop3_b32 v9, v7, s5, v8 bitop3:0xde
	s_lshl_b32 s5, s18, 5
	s_add_i32 s33, s38, s33
	s_and_b32 s5, s5, 0x60
	s_ashr_i32 s49, s33, 6
	s_lshl_b32 s18, s5, 7
	s_cmp_gt_i32 s38, 63
	v_add_u32_e32 v0, v2, v0
	s_waitcnt vmcnt(6)
	s_cselect_b64 s[46:47], -1, 0
	s_add_i32 s70, s49, -2
	v_add_lshl_u32 v128, v0, v1, 1
	v_add_u32_e32 v0, v5, v3
	s_cmpk_lt_u32 s4, 0x100
	v_lshl_add_u64 v[182:183], s[36:37], 0, v[128:129]
	v_add_lshl_u32 v128, v0, v4, 1
	v_bitop3_b32 v203, s18, v7, v8 bitop3:0xf6
	s_cselect_b64 s[50:51], -1, 0
	s_ashr_i32 s71, s20, 31
	s_ashr_i32 s72, s60, 31
	v_or_b32_e32 v204, s5, v6
	v_lshl_add_u64 v[184:185], s[36:37], 0, v[128:129]
	s_mov_b32 s73, 0
	v_add_u32_e32 v205, 0, v9
	s_barrier
	s_branch .LBB0_1153

.LBB0_1628:
	s_load_dwordx2 s[10:11], s[0:1], 0x118
	v_and_b32_e32 v147, 15, v146
	v_lshlrev_b32_e32 v144, 2, v147
	s_waitcnt lgkmcnt(0)
	s_add_u32 s0, s10, 0xec00000
	s_addc_u32 s1, s11, 0
	s_add_u32 s2, s10, 0x210000
	s_addc_u32 s3, s11, 0
	s_add_u32 s12, s10, 0x2100000
	s_addc_u32 s13, s11, 0
	s_andn2_b64 vcc, exec, s[14:15]
	s_cbranch_vccnz .LBB0_1670
	v_bfe_i32 v2, v145, 27, 1
	v_lshlrev_b32_e32 v0, 4, v145
	v_lshrrev_b32_e32 v2, 22, v2
	v_add_u32_e32 v2, v0, v2
	v_and_b32_e32 v2, 0xfffffc00, v2
	v_sub_u32_e32 v2, v0, v2
	v_ashrrev_i32_e32 v1, 31, v145
	v_lshrrev_b32_e32 v3, 4, v2
	v_lshrrev_b32_e32 v1, 26, v1
	v_bitop3_b32 v2, v3, v2, 32 bitop3:0x6c
	v_add_u32_e32 v1, v145, v1
	v_ashrrev_i32_e32 v4, 31, v2
	v_ashrrev_i32_e32 v1, 6, v1
	v_lshrrev_b32_e32 v4, 26, v4
	v_lshlrev_b32_e32 v3, 3, v1
	v_add_u32_e32 v4, v2, v4
	v_and_b32_e32 v3, -16, v3
	v_ashrrev_i32_e32 v5, 6, v4
	v_lshlrev_b32_e32 v1, 5, v1
	v_add_u32_e32 v3, v5, v3
	v_and_b32_e32 v12, 32, v1
	v_and_b32_e32 v1, 0xc0, v4
	v_sub_u32_e32 v1, v2, v1
	v_mov_b32_e32 v6, 1
	v_lshlrev_b32_e32 v2, 1, v3
	v_lshrrev_b32_e32 v4, 2, v3
	v_and_b32_e32 v5, 3, v5
	s_mov_b32 s14, 0x7fffffe0
	v_ashrrev_i16_sdwa v1, v6, sext(v1) dst_sel:DWORD dst_unused:UNUSED_PAD src0_sel:DWORD src1_sel:BYTE_0
	v_and_b32_e32 v2, 24, v2
	v_and_b32_e32 v4, 4, v4
	v_and_or_b32 v5, v3, s14, v5
	v_bfe_i32 v13, v1, 0, 16
	v_or3_b32 v2, v5, v4, v2
	v_add_u32_e32 v1, v12, v13
	v_mul_lo_u32 v14, v3, s26
	v_mul_lo_u32 v2, v2, s26
	v_add_u32_e32 v0, 0x2000, v0
	v_add_lshl_u32 v130, v1, v14, 1
	v_add_lshl_u32 v132, v2, v1, 1
	v_ashrrev_i32_e32 v1, 31, v0
	v_lshrrev_b32_e32 v1, 22, v1
	v_add_u32_e32 v1, v0, v1
	v_ashrrev_i32_e32 v1, 10, v1
	s_add_u32 s6, s10, 0x1ee00000
	v_mul_i32_i24_e32 v2, 0x400, v1
	s_addc_u32 s7, s11, 0
	v_sub_u32_e32 v0, v0, v2
	s_ashr_i32 s27, s26, 31
	v_lshrrev_b32_e32 v2, 4, v0
	s_lshl_b64 s[22:23], s[26:27], 9
	s_ashr_i32 s20, s65, 31
	v_bitop3_b32 v0, v2, v0, 32 bitop3:0x6c
	s_mul_i32 s20, s22, s20
	s_mul_hi_u32 s24, s22, s65
	v_ashrrev_i32_e32 v3, 31, v0
	s_add_i32 s20, s24, s20
	s_lshr_b64 s[24:25], s[26:27], 23
	v_lshrrev_b32_e32 v3, 26, v3
	s_mul_i32 s25, s24, s65
	v_lshlrev_b32_e32 v2, 3, v1
	v_add_u32_e32 v3, v0, v3
	s_add_i32 s38, s20, s25
	s_ashr_i32 s20, s62, 31
	v_and_b32_e32 v2, -16, v2
	v_ashrrev_i32_e32 v4, 6, v3
	s_mul_i32 s20, s22, s20
	s_mul_hi_u32 s25, s22, s62
	s_ashr_i32 s36, s33, 6
	v_add_u32_e32 v2, v4, v2
	v_lshlrev_b32_e32 v1, 5, v1
	v_and_b32_e32 v4, 3, v4
	s_add_i32 s20, s25, s20
	s_mul_i32 s24, s24, s62
	v_and_b32_e32 v15, 32, v1
	v_and_b32_e32 v1, 0xc0, v3
	v_and_or_b32 v4, v2, s14, v4
	s_ashr_i32 s37, s33, 8
	s_lshl_b64 s[14:15], s[26:27], 8
	s_lshl_b32 s18, s36, 10
	s_add_i32 s20, s20, s24
	s_mul_i32 s24, s22, s62
	v_sub_u32_e32 v0, v0, v1
	v_lshlrev_b32_e32 v1, 1, v2
	v_lshrrev_b32_e32 v3, 2, v2
	s_add_u32 s28, s12, s24
	v_ashrrev_i16_sdwa v0, v6, sext(v0) dst_sel:DWORD dst_unused:UNUSED_PAD src0_sel:DWORD src1_sel:BYTE_0
	v_and_b32_e32 v1, 24, v1
	v_and_b32_e32 v3, 4, v3
	s_addc_u32 s29, s13, s20
	s_add_i32 s20, s18, 0
	v_bfe_i32 v16, v0, 0, 16
	v_or3_b32 v1, v4, v3, v1
	s_add_i32 m0, s20, 0x10000
	v_add_u32_e32 v0, v15, v16
	v_mul_lo_u32 v1, v1, s26
	global_load_lds_dwordx4 v132, s[28:29]
	s_add_i32 m0, s20, 0x12000
	v_add_lshl_u32 v136, v1, v0, 1
	s_add_u32 s24, s28, s14
	global_load_lds_dwordx4 v136, s[28:29]
	s_addc_u32 s25, s29, s15
	s_add_i32 m0, s20, 0x14000
	s_mul_i32 s39, s22, s65
	global_load_lds_dwordx4 v132, s[24:25]
	s_add_i32 m0, s20, 0x16000
	s_add_u32 s46, s6, s39
	v_mov_b32_e32 v133, v129
	v_mov_b32_e32 v137, v129
	s_addc_u32 s47, s7, s38
	s_add_i32 s48, s20, 0x2000
	v_mul_lo_u32 v17, v2, s26
	v_lshl_add_u64 v[4:5], s[24:25], 0, v[132:133]
	v_lshl_add_u64 v[6:7], s[24:25], 0, v[136:137]
	global_load_lds_dwordx4 v136, s[24:25]
	s_mov_b32 m0, s20
	s_add_u32 s24, s46, s14
	v_add_lshl_u32 v134, v0, v17, 1
	global_load_lds_dwordx4 v130, s[46:47]
	s_mov_b32 m0, s48
	s_addc_u32 s25, s47, s15
	s_add_i32 s49, s20, 0x4000
	global_load_lds_dwordx4 v134, s[46:47]
	s_mov_b32 m0, s49
	s_add_i32 s50, s20, 0x6000
	global_load_lds_dwordx4 v130, s[24:25]
	s_mov_b32 m0, s50
	v_mov_b32_e32 v131, v129
	global_load_lds_dwordx4 v134, s[24:25]
	v_mov_b32_e32 v135, v129
	s_cmp_eq_u32 s37, 1
	v_lshl_add_u64 v[0:1], s[28:29], 0, v[132:133]
	v_lshl_add_u64 v[2:3], s[28:29], 0, v[136:137]
	v_lshl_add_u64 v[8:9], s[46:47], 0, v[130:131]
	v_lshl_add_u64 v[10:11], s[46:47], 0, v[134:135]
	s_cselect_b64 s[24:25], -1, 0
	s_add_i32 m0, s20, 0x18000
	v_lshl_add_u64 v[0:1], v[0:1], 0, s[34:35]
	global_load_lds_dwordx4 v[0:1], off
	v_lshl_add_u64 v[0:1], v[2:3], 0, s[34:35]
	s_add_i32 m0, s20, 0x1a000
	s_add_i32 s51, s20, 0x8000
	global_load_lds_dwordx4 v[0:1], off
	v_lshl_add_u64 v[0:1], v[8:9], 0, s[34:35]
	s_mov_b32 m0, s51
	s_add_i32 s52, s20, 0xa000
	global_load_lds_dwordx4 v[0:1], off
	v_lshl_add_u64 v[0:1], v[10:11], 0, s[34:35]
	s_mov_b32 m0, s52
	s_lshr_b32 s27, s27, 26
	global_load_lds_dwordx4 v[0:1], off
	s_add_i32 m0, s20, 0x1c000
	v_lshl_add_u64 v[0:1], v[4:5], 0, s[34:35]
	global_load_lds_dwordx4 v[0:1], off
	v_lshl_add_u64 v[0:1], v[6:7], 0, s[34:35]
	s_add_i32 m0, s20, 0x1e000
	s_add_i32 s27, s26, s27
	global_load_lds_dwordx4 v[0:1], off
	s_cmp_lg_u32 s37, 1
	s_cbranch_scc1 .Lpro_4
	s_barrier
.Lpro_4:
	s_waitcnt vmcnt(8)
	s_barrier
	v_bfe_u32 v0, v146, 4, 2
	v_lshlrev_b32_e32 v2, 4, v0
	s_and_b32 s40, s36, 3
	s_ashr_i32 s53, s27, 6
	v_lshl_or_b32 v2, v147, 6, v2
	s_lshl_b32 s27, s37, 13
	v_and_b32_e32 v3, 32, v144
	v_bitop3_b32 v4, v2, s27, v3 bitop3:0xde
	s_lshl_b32 s27, s40, 12
	s_cmp_gt_i32 s26, 63
	v_bitop3_b32 v149, s27, v2, v3 bitop3:0xf6
	s_cselect_b64 s[26:27], -1, 0
	s_add_i32 s56, s53, -2
	v_lshlrev_b32_e32 v1, 3, v0
	s_cmpk_lt_u32 s33, 0x100
	v_cmp_eq_u32_e64 s[38:39], 0, v0
	v_add_u32_e32 v0, v14, v12
	v_lshl_or_b32 v148, s37, 6, v147
	s_waitcnt vmcnt(6)
	s_cselect_b64 s[36:37], -1, 0
	s_ashr_i32 s58, s4, 31
	s_ashr_i32 s59, s5, 31
	s_lshl_b32 s33, s40, 2
	v_add_lshl_u32 v128, v0, v13, 1
	v_add_u32_e32 v0, v17, v15
	s_add_u32 s60, s2, s33
	v_lshl_add_u64 v[138:139], s[14:15], 0, v[128:129]
	v_add_lshl_u32 v128, v0, v16, 1
	v_lshl_or_b32 v150, s40, 5, v1
	s_mov_b32 s57, 0
	s_addc_u32 s61, s3, 0
	v_lshl_add_u64 v[140:141], s[14:15], 0, v[128:129]
	v_add_u32_e32 v151, 0, v4
	s_barrier
	s_branch .LBB0_1634

.LBB0_1742:
	s_add_u32 s70, s58, 0x12c80000
	s_addc_u32 s71, s59, 0
	s_add_u32 s10, s58, 0x100000
	v_readlane_b32 s6, v255, 27
	s_addc_u32 s11, s59, 0
	v_readlane_b32 s7, v255, 28
	s_and_b64 s[4:5], s[6:7], exec
	s_cselect_b32 s4, 0x600000, 0
	s_add_u32 s4, s58, s4
	s_addc_u32 s5, s59, 0
	s_add_u32 s12, s4, 0xc00000
	s_addc_u32 s13, s5, 0
	s_and_b64 s[4:5], s[6:7], exec
	s_cselect_b32 s4, 0x100, 0
	s_add_u32 s72, s60, s4
	s_addc_u32 s73, s61, 0
	s_add_u32 s85, s62, s4
	s_addc_u32 s86, s63, 0
	s_and_b64 s[4:5], s[6:7], exec
	s_cselect_b32 s4, 0x100000, 0
	s_add_u32 s4, s56, s4
	s_addc_u32 s5, s57, 0
	v_and_b32_e32 v194, 15, v157
	s_add_u32 s87, s4, 0x28100000
	s_addc_u32 s88, s5, 0
	s_andn2_b64 vcc, exec, s[14:15]
	v_lshlrev_b32_e32 v146, 2, v194
	s_cbranch_vccnz .LBB0_1830
	s_waitcnt vmcnt(3)
	v_bfe_i32 v2, v147, 27, 1
	v_lshlrev_b32_e32 v0, 4, v147
	v_lshrrev_b32_e32 v2, 22, v2
	v_add_u32_e32 v2, v0, v2
	v_and_b32_e32 v2, 0xfffffc00, v2
	v_sub_u32_e32 v2, v0, v2
	v_ashrrev_i32_e32 v1, 31, v147
	v_lshrrev_b32_e32 v3, 4, v2
	v_lshrrev_b32_e32 v1, 26, v1
	v_bitop3_b32 v2, v3, v2, 32 bitop3:0x6c
	v_add_u32_e32 v1, v147, v1
	s_waitcnt vmcnt(2)
	v_ashrrev_i32_e32 v4, 31, v2
	v_ashrrev_i32_e32 v1, 6, v1
	v_lshrrev_b32_e32 v4, 26, v4
	v_lshlrev_b32_e32 v3, 3, v1
	v_add_u32_e32 v4, v2, v4
	v_and_b32_e32 v3, -16, v3
	v_ashrrev_i32_e32 v5, 6, v4
	v_lshlrev_b32_e32 v1, 5, v1
	v_add_u32_e32 v3, v5, v3
	s_waitcnt vmcnt(0)
	v_and_b32_e32 v12, 32, v1
	v_and_b32_e32 v1, 0xc0, v4
	v_sub_u32_e32 v1, v2, v1
	v_mov_b32_e32 v6, 1
	v_lshlrev_b32_e32 v2, 1, v3
	v_lshrrev_b32_e32 v4, 2, v3
	v_and_b32_e32 v5, 3, v5
	s_mov_b32 s4, 0x7fffffe0
	v_ashrrev_i16_sdwa v1, v6, sext(v1) dst_sel:DWORD dst_unused:UNUSED_PAD src0_sel:DWORD src1_sel:BYTE_0
	v_and_b32_e32 v2, 24, v2
	v_and_b32_e32 v4, 4, v4
	v_and_or_b32 v5, v3, s4, v5
	v_bfe_i32 v13, v1, 0, 16
	v_or3_b32 v2, v5, v4, v2
	v_add_u32_e32 v1, v12, v13
	v_mul_lo_u32 v14, s26, v3
	v_mul_lo_u32 v2, s26, v2
	v_add_u32_e32 v0, 0x2000, v0
	v_add_lshl_u32 v148, v14, v1, 1
	v_add_lshl_u32 v150, v2, v1, 1
	v_ashrrev_i32_e32 v1, 31, v0
	v_lshrrev_b32_e32 v1, 22, v1
	v_add_u32_e32 v1, v0, v1
	v_ashrrev_i32_e32 v1, 10, v1
	v_mul_i32_i24_e32 v2, 0x400, v1
	v_sub_u32_e32 v0, v0, v2
	v_lshrrev_b32_e32 v2, 4, v0
	v_bitop3_b32 v0, v2, v0, 32 bitop3:0x6c
	v_ashrrev_i32_e32 v3, 31, v0
	v_lshrrev_b32_e32 v3, 26, v3
	v_lshlrev_b32_e32 v2, 3, v1
	v_add_u32_e32 v3, v0, v3
	v_and_b32_e32 v2, -16, v2
	v_ashrrev_i32_e32 v4, 6, v3
	s_ashr_i32 s33, s18, 6
	v_add_u32_e32 v2, v4, v2
	v_and_b32_e32 v4, 3, v4
	s_ashr_i32 s27, s26, 31
	v_and_or_b32 v4, v2, s4, v4
	s_ashr_i32 s38, s18, 8
	s_lshl_b64 s[14:15], s[26:27], 8
	s_lshl_b64 s[22:23], s[26:27], 9
	s_lshl_b32 s4, s33, 10
	s_add_u32 s5, s58, 0xec00000
	s_addc_u32 s6, s59, 0
	s_ashr_i32 s7, s45, 31
	s_mul_i32 s7, s22, s7
	s_mul_hi_u32 s24, s22, s45
	s_add_i32 s7, s24, s7
	s_lshr_b64 s[24:25], s[26:27], 23
	s_mul_i32 s25, s24, s45
	s_add_i32 s36, s7, s25
	s_ashr_i32 s7, s44, 31
	s_mul_i32 s7, s22, s7
	s_mul_hi_u32 s25, s22, s44
	v_lshlrev_b32_e32 v1, 5, v1
	s_add_i32 s7, s25, s7
	s_mul_i32 s24, s24, s44
	v_and_b32_e32 v15, 32, v1
	v_and_b32_e32 v1, 0xc0, v3
	s_add_i32 s7, s7, s24
	s_mul_i32 s24, s22, s44
	v_sub_u32_e32 v0, v0, v1
	v_lshlrev_b32_e32 v1, 1, v2
	v_lshrrev_b32_e32 v3, 2, v2
	s_add_u32 s28, s12, s24
	v_ashrrev_i16_sdwa v0, v6, sext(v0) dst_sel:DWORD dst_unused:UNUSED_PAD src0_sel:DWORD src1_sel:BYTE_0
	v_and_b32_e32 v1, 24, v1
	v_and_b32_e32 v3, 4, v3
	s_addc_u32 s29, s13, s7
	s_add_i32 s7, s4, 0
	v_bfe_i32 v16, v0, 0, 16
	v_or3_b32 v1, v4, v3, v1
	s_add_i32 m0, s7, 0x10000
	v_add_u32_e32 v0, v15, v16
	v_mul_lo_u32 v1, s26, v1
	global_load_lds_dwordx4 v150, s[28:29]
	s_add_i32 m0, s7, 0x12000
	v_add_lshl_u32 v154, v1, v0, 1
	s_add_u32 s24, s28, s14
	global_load_lds_dwordx4 v154, s[28:29]
	s_addc_u32 s25, s29, s15
	s_add_i32 m0, s7, 0x14000
	s_mul_i32 s37, s22, s45
	global_load_lds_dwordx4 v150, s[24:25]
	s_add_i32 m0, s7, 0x16000
	s_add_u32 s42, s5, s37
	s_addc_u32 s43, s6, s36
	s_add_i32 s48, s7, 0x2000
	v_mul_lo_u32 v17, s26, v2
	global_load_lds_dwordx4 v154, s[24:25]
	s_mov_b32 m0, s7
	s_add_u32 s36, s42, s14
	v_add_lshl_u32 v152, v17, v0, 1
	global_load_lds_dwordx4 v148, s[42:43]
	s_mov_b32 m0, s48
	s_addc_u32 s37, s43, s15
	s_add_i32 s49, s7, 0x4000
	global_load_lds_dwordx4 v152, s[42:43]
	s_mov_b32 m0, s49
	s_add_i32 s89, s7, 0x6000
	global_load_lds_dwordx4 v148, s[36:37]
	s_mov_b32 m0, s89
	v_mov_b32_e32 v151, v129
	global_load_lds_dwordx4 v152, s[36:37]
	v_mov_b32_e32 v155, v129
	v_mov_b32_e32 v149, v129
	v_mov_b32_e32 v153, v129
	s_cmp_eq_u32 s38, 1
	v_lshl_add_u64 v[8:9], s[28:29], 0, v[150:151]
	v_lshl_add_u64 v[4:5], s[28:29], 0, v[154:155]
	v_lshl_add_u64 v[2:3], s[24:25], 0, v[150:151]
	v_lshl_add_u64 v[0:1], s[24:25], 0, v[154:155]
	v_lshl_add_u64 v[6:7], s[42:43], 0, v[148:149]
	s_cselect_b64 s[24:25], -1, 0
	v_lshl_add_u64 v[10:11], s[42:43], 0, v[152:153]
	s_lshr_b32 s27, s27, 26
	s_and_b32 s90, s33, 3
	s_add_i32 s27, s26, s27
	v_readlane_b32 s36, v255, 27
	s_ashr_i32 s91, s27, 6
	s_lshl_b32 s92, s38, 6
	s_lshl_b32 s27, s38, 13
	s_lshl_b32 s33, s90, 12
	v_readlane_b32 s37, v255, 28
	s_and_b64 s[36:37], s[36:37], exec
	s_cselect_b32 s36, 0x8000000, 0
	s_add_u32 s39, s56, s36
	s_addc_u32 s40, s57, 0
	s_add_u32 s93, s39, 0x8100000
	s_addc_u32 s94, s40, 0
	s_add_i32 m0, s7, 0x18000
	v_lshl_add_u64 v[8:9], v[8:9], 0, s[34:35]
	global_load_lds_dwordx4 v[8:9], off
	v_lshl_add_u64 v[4:5], v[4:5], 0, s[34:35]
	s_add_i32 m0, s7, 0x1a000
	s_add_i32 s95, s7, 0x8000
	global_load_lds_dwordx4 v[4:5], off
	v_lshl_add_u64 v[4:5], v[6:7], 0, s[34:35]
	s_mov_b32 m0, s95
	s_add_i32 s96, s7, 0xa000
	global_load_lds_dwordx4 v[4:5], off
	v_lshl_add_u64 v[4:5], v[10:11], 0, s[34:35]
	s_mov_b32 m0, s96
	v_lshl_add_u64 v[2:3], v[2:3], 0, s[34:35]
	global_load_lds_dwordx4 v[4:5], off
	s_add_i32 m0, s7, 0x1c000
	v_lshl_add_u64 v[0:1], v[0:1], 0, s[34:35]
	global_load_lds_dwordx4 v[2:3], off
	s_add_i32 m0, s7, 0x1e000
	s_cmp_gt_i32 s26, 63
	global_load_lds_dwordx4 v[0:1], off
	v_lshrrev_b32_e32 v0, 1, v157
	v_and_b32_e32 v156, 24, v0
	v_lshlrev_b32_e32 v0, 1, v156
	v_lshl_or_b32 v0, v194, 6, v0
	v_and_b32_e32 v1, 32, v146
	v_bitop3_b32 v2, v0, s27, v1 bitop3:0xde
	s_cselect_b64 s[26:27], -1, 0
	s_cmp_lg_u32 s38, 1
	s_cbranch_scc1 .Lpro_5
	s_barrier
.Lpro_5:
	s_waitcnt vmcnt(8)
	s_barrier
	s_add_i32 s97, s91, -2
	s_cmpk_lt_u32 s18, 0x100
	s_cselect_b64 s[36:37], -1, 0
	s_lshl_b32 s18, s38, 8
	s_add_i32 s18, s18, 0
	s_add_i32 s18, s18, 0x20800
	v_bitop3_b32 v195, s33, v0, v1 bitop3:0xf6
	v_lshlrev_b32_e32 v128, 2, v156
	s_add_u32 s50, s87, 0x200000
	v_add_u32_e32 v0, v14, v12
	s_waitcnt vmcnt(6)
	v_lshl_add_u64 v[158:159], s[10:11], 0, v[128:129]
	s_addc_u32 s51, s88, 0
	v_add_lshl_u32 v128, v0, v13, 1
	v_add_u32_e32 v0, v17, v15
	s_add_u32 s56, s39, 0x18100000
	v_lshl_add_u64 v[160:161], s[14:15], 0, v[128:129]
	v_add_lshl_u32 v128, v0, v16, 1
	s_mov_b32 s53, 0
	v_or_b32_e32 v196, 0x800, v194
	v_add_u32_e32 v197, s18, v146
	s_addc_u32 s57, s40, 0
	v_lshl_add_u64 v[162:163], s[14:15], 0, v[128:129]
	v_add_u32_e32 v202, 0, v2
	v_lshlrev_b32_e32 v203, 2, v156
	s_barrier
	s_branch .LBB0_1748

.LBB0_1833:
	s_ashr_i32 s15, s6, 2
	s_lshl_b32 s2, s15, 6
	s_lshl_b32 s10, s15, 5
	s_and_b32 s7, s2, 0xffffff00
	s_and_b32 s10, s10, 64
	s_or_b32 s7, s10, s7
	v_or_b32_e32 v0, s7, v76
	s_or_b32 s10, s15, 1
	v_ashrrev_i32_e32 v1, 31, v0
	s_lshl_b32 s7, s10, 6
	s_lshl_b32 s10, s10, 5
	v_lshlrev_b64 v[16:17], 11, v[0:1]
	v_or_b32_e32 v0, 0x80, v0
	s_and_b32 s11, s7, 0xffffff00
	s_and_b32 s10, s10, 0x60
	v_ashrrev_i32_e32 v1, 31, v0
	s_or_b32 s10, s10, s11
	s_and_b32 s3, s5, 0xe0
	v_lshlrev_b64 v[18:19], 11, v[0:1]
	v_or_b32_e32 v0, s10, v76
	v_ashrrev_i32_e32 v1, 31, v0
	v_add_u32_e32 v70, s3, v77
	v_lshlrev_b64 v[20:21], 11, v[0:1]
	v_or_b32_e32 v0, 0x80, v0
	v_add_u32_e32 v72, 0x8000, v70
	v_ashrrev_i32_e32 v1, 31, v0
	v_ashrrev_i32_e32 v73, 31, v72
	v_lshlrev_b64 v[22:23], 11, v[0:1]
	v_lshlrev_b64 v[0:1], 6, v[72:73]
	v_lshl_add_u64 v[12:13], s[0:1], 0, v[0:1]
	global_load_dwordx4 v[32:35], v[12:13], off offset:32
	global_load_dwordx4 v[36:39], v[12:13], off offset:48
	global_load_dwordx4 v[40:43], v[12:13], off
	s_nop 0
	global_load_dwordx4 v[44:47], v[12:13], off offset:16
	v_or_b32_e32 v24, s3, v76
	v_lshlrev_b32_e32 v128, 11, v24
	v_lshl_add_u64 v[74:75], v[64:65], 0, v[128:129]
	v_lshl_add_u64 v[142:143], v[66:67], 0, v[16:17]
	v_lshl_add_u64 v[144:145], v[66:67], 0, v[18:19]
	v_lshl_add_u64 v[152:153], v[66:67], 0, v[20:21]
	v_lshl_add_u64 v[160:161], v[66:67], 0, v[22:23]
	global_load_dwordx4 v[16:19], v[74:75], off
	global_load_dwordx4 v[0:3], v[142:143], off
	global_load_dwordx4 v[4:7], v[144:145], off
	global_load_dwordx4 v[8:11], v[152:153], off
	global_load_dwordx4 v[20:23], v[160:161], off
	global_load_dwordx4 v[80:83], v[74:75], off offset:32
	global_load_dwordx4 v[84:87], v[142:143], off offset:32
	global_load_dwordx4 v[88:91], v[144:145], off offset:32
	global_load_dwordx4 v[92:95], v[152:153], off offset:32
	global_load_dwordx4 v[96:99], v[160:161], off offset:32
	global_load_dwordx4 v[100:103], v[74:75], off offset:64
	global_load_dwordx4 v[104:107], v[142:143], off offset:64
	global_load_dwordx4 v[108:111], v[144:145], off offset:64
	global_load_dwordx4 v[112:115], v[152:153], off offset:64
	global_load_dwordx4 v[116:119], v[160:161], off offset:64
	global_load_dwordx4 v[120:123], v[74:75], off offset:96
	global_load_dwordx4 v[124:127], v[142:143], off offset:96
	global_load_dwordx4 v[130:133], v[144:145], off offset:96
	global_load_dwordx4 v[134:137], v[152:153], off offset:96
	global_load_dwordx4 v[138:141], v[160:161], off offset:96
	s_waitcnt vmcnt(20)
	v_pk_add_f32 v[34:35], v[34:35], v[38:39]
	v_pk_add_f32 v[32:33], v[32:33], v[36:37]
	v_pk_add_f32 v[42:43], v[42:43], v[46:47]
	v_pk_add_f32 v[40:41], v[40:41], v[44:45]
	v_pk_add_f32 v[34:35], v[42:43], v[34:35]
	v_pk_add_f32 v[32:33], v[40:41], v[32:33]
	s_nop 0
	v_pk_mov_b32 v[36:37], v[32:33], v[34:35] op_sel:[1,0]
	v_mov_b32_e32 v33, v35
	v_pk_add_f32 v[32:33], v[36:37], v[32:33]
	s_nop 0
	v_add_f32_e32 v32, v32, v33
	v_fmamk_f32 v32, v32, 0x3a800000, v242
	v_cmp_gt_f32_e32 vcc, s19, v32
	v_mul_f32_e32 v33, 0x4f800000, v32
	s_nop 0
	v_cndmask_b32_e32 v32, v32, v33, vcc
	v_sqrt_f32_e32 v33, v32
	s_nop 0
	v_add_u32_e32 v34, -1, v33
	v_fma_f32 v35, -v34, v33, v32
	v_cmp_ge_f32_e64 s[40:41], 0, v35
	v_add_u32_e32 v35, 1, v33
	s_nop 0
	v_cndmask_b32_e64 v34, v33, v34, s[40:41]
	v_fma_f32 v33, -v35, v33, v32
	v_cmp_lt_f32_e64 s[40:41], 0, v33
	s_nop 1
	v_cndmask_b32_e64 v33, v34, v35, s[40:41]
	v_mul_f32_e32 v34, 0x37800000, v33
	v_cndmask_b32_e32 v33, v33, v34, vcc
	v_cmp_class_f32_e32 vcc, v32, v243
	s_nop 1
	v_cndmask_b32_e32 v71, v33, v32, vcc
	s_waitcnt vmcnt(0)
	v_mfma_f32_32x32x16_bf16 v[32:47], v[16:19], v[0:3], 0
	v_mfma_f32_32x32x16_bf16 v[48:63], v[16:19], v[4:7], 0
	v_mfma_f32_32x32x16_bf16 v[0:15], v[16:19], v[8:11], 0
	v_mfma_f32_32x32x16_bf16 v[16:31], v[16:19], v[20:23], 0
	v_mfma_f32_32x32x16_bf16 v[32:47], v[80:83], v[84:87], v[32:47]
	v_mfma_f32_32x32x16_bf16 v[48:63], v[80:83], v[88:91], v[48:63]
	v_mfma_f32_32x32x16_bf16 v[0:15], v[80:83], v[92:95], v[0:15]
	v_mfma_f32_32x32x16_bf16 v[16:31], v[80:83], v[96:99], v[16:31]
	v_mfma_f32_32x32x16_bf16 v[32:47], v[100:103], v[104:107], v[32:47]
	v_mfma_f32_32x32x16_bf16 v[48:63], v[100:103], v[108:111], v[48:63]
	v_mfma_f32_32x32x16_bf16 v[0:15], v[100:103], v[112:115], v[0:15]
	v_mfma_f32_32x32x16_bf16 v[16:31], v[100:103], v[116:119], v[16:31]
	v_mfma_f32_32x32x16_bf16 v[32:47], v[120:123], v[124:127], v[32:47]
	v_mfma_f32_32x32x16_bf16 v[48:63], v[120:123], v[130:133], v[48:63]
	v_mfma_f32_32x32x16_bf16 v[0:15], v[120:123], v[134:137], v[0:15]
	v_mfma_f32_32x32x16_bf16 v[16:31], v[120:123], v[138:141], v[16:31]
	global_load_dwordx4 v[80:83], v[74:75], off offset:128
	global_load_dwordx4 v[84:87], v[74:75], off offset:160
	global_load_dwordx4 v[88:91], v[142:143], off offset:128
	global_load_dwordx4 v[92:95], v[142:143], off offset:160
	global_load_dwordx4 v[96:99], v[144:145], off offset:128
	global_load_dwordx4 v[100:103], v[144:145], off offset:160
	global_load_dwordx4 v[104:107], v[152:153], off offset:128
	global_load_dwordx4 v[108:111], v[152:153], off offset:160
	global_load_dwordx4 v[112:115], v[160:161], off offset:128
	global_load_dwordx4 v[116:119], v[160:161], off offset:160
	global_load_dwordx4 v[120:123], v[74:75], off offset:192
	global_load_dwordx4 v[124:127], v[74:75], off offset:224
	global_load_dwordx4 v[130:133], v[142:143], off offset:192
	global_load_dwordx4 v[134:137], v[142:143], off offset:224
	global_load_dwordx4 v[138:141], v[144:145], off offset:192
	s_nop 0
	global_load_dwordx4 v[142:145], v[144:145], off offset:224
	s_nop 0
	global_load_dwordx4 v[148:151], v[152:153], off offset:192
	s_nop 0
	global_load_dwordx4 v[152:155], v[152:153], off offset:224
	s_nop 0
	global_load_dwordx4 v[156:159], v[160:161], off offset:192
	s_nop 0
	global_load_dwordx4 v[160:163], v[160:161], off offset:224
	s_waitcnt vmcnt(0)
	v_mfma_f32_32x32x16_bf16 v[32:47], v[80:83], v[88:91], v[32:47]
	v_mfma_f32_32x32x16_bf16 v[48:63], v[80:83], v[96:99], v[48:63]
	v_mfma_f32_32x32x16_bf16 v[0:15], v[80:83], v[104:107], v[0:15]
	v_mfma_f32_32x32x16_bf16 v[16:31], v[80:83], v[112:115], v[16:31]
	v_mfma_f32_32x32x16_bf16 v[32:47], v[84:87], v[92:95], v[32:47]
	v_mfma_f32_32x32x16_bf16 v[48:63], v[84:87], v[100:103], v[48:63]
	v_mfma_f32_32x32x16_bf16 v[0:15], v[84:87], v[108:111], v[0:15]
	v_mfma_f32_32x32x16_bf16 v[16:31], v[84:87], v[116:119], v[16:31]
	v_mfma_f32_32x32x16_bf16 v[32:47], v[120:123], v[130:133], v[32:47]
	v_mfma_f32_32x32x16_bf16 v[48:63], v[120:123], v[138:141], v[48:63]
	v_mfma_f32_32x32x16_bf16 v[0:15], v[120:123], v[148:151], v[0:15]
	v_mfma_f32_32x32x16_bf16 v[16:31], v[120:123], v[156:159], v[16:31]
	v_mfma_f32_32x32x16_bf16 v[32:47], v[124:127], v[134:137], v[32:47]
	v_mfma_f32_32x32x16_bf16 v[48:63], v[124:127], v[142:145], v[48:63]
	v_mfma_f32_32x32x16_bf16 v[0:15], v[124:127], v[152:155], v[0:15]
	v_mfma_f32_32x32x16_bf16 v[16:31], v[124:127], v[160:163], v[16:31]
	s_nop 9
	ds_write2_b32 v78, v32, v48 offset1:32
	ds_write2_b32 v78, v33, v49 offset0:65 offset1:97
	ds_write2_b32 v78, v34, v50 offset0:130 offset1:162
	ds_write2_b32 v78, v35, v51 offset0:195 offset1:227
	v_add_u32_e32 v48, 0x800, v78
	v_add_u32_e32 v49, 0x1000, v78
	v_add_u32_e32 v50, 0x1800, v78
	ds_write2_b32 v48, v36, v52 offset0:8 offset1:40
	ds_write2_b32 v48, v37, v53 offset0:73 offset1:105
	ds_write2_b32 v48, v38, v54 offset0:138 offset1:170
	ds_write2_b32 v48, v39, v55 offset0:203 offset1:235
	ds_write2_b32 v49, v40, v56 offset0:16 offset1:48
	ds_write2_b32 v49, v41, v57 offset0:81 offset1:113
	ds_write2_b32 v49, v42, v58 offset0:146 offset1:178
	ds_write2_b32 v49, v43, v59 offset0:211 offset1:243
	ds_write2_b32 v50, v44, v60 offset0:24 offset1:56
	ds_write2_b32 v50, v45, v61 offset0:89 offset1:121
	ds_write2_b32 v50, v46, v62 offset0:154 offset1:186
	ds_write2_b32 v50, v47, v63 offset0:219 offset1:251
	s_waitcnt lgkmcnt(0)
	s_barrier
	ds_read2_b32 v[32:33], v79 offset1:1
	v_add_u32_e32 v46, 0x2080, v79
	v_add_u32_e32 v47, 0x4100, v79
	ds_read2_b32 v[34:35], v46 offset1:1
	ds_read2_b32 v[36:37], v47 offset1:1
	ds_read2_b32 v[38:39], v79 offset0:2 offset1:3
	v_add_u32_e32 v52, 0x6180, v79
	s_waitcnt lgkmcnt(0)
	v_pk_add_f32 v[32:33], v[32:33], 0 op_sel_hi:[1,0]
	v_add_u32_e32 v53, 0x8200, v79
	v_pk_add_f32 v[32:33], v[32:33], v[34:35]
	v_add_u32_e32 v54, 0xa280, v79
	v_add_u32_e32 v51, 0xc300, v79
	ds_read2_b32 v[34:35], v52 offset1:1
	ds_read2_b32 v[40:41], v53 offset1:1
	ds_read2_b32 v[42:43], v54 offset1:1
	ds_read2_b32 v[44:45], v51 offset1:1
	v_pk_add_f32 v[32:33], v[32:33], v[36:37]
	v_add_u32_e32 v55, 0xe380, v79
	v_div_scale_f32 v74, s[10:11], v71, v71, 1.0
	s_waitcnt lgkmcnt(3)
	v_pk_add_f32 v[32:33], v[32:33], v[34:35]
	ds_read2_b32 v[34:35], v55 offset1:1
	v_rcp_f32_e32 v75, v74
	s_waitcnt lgkmcnt(3)
	v_pk_add_f32 v[32:33], v[32:33], v[40:41]
	v_add_u32_e32 v56, 0x2088, v79
	s_waitcnt lgkmcnt(2)
	v_pk_add_f32 v[32:33], v[32:33], v[42:43]
	v_add_u32_e32 v57, 0x4108, v79
	v_add_u32_e32 v58, 0x6188, v79
	ds_read2_b32 v[36:37], v56 offset1:1
	ds_read2_b32 v[40:41], v57 offset1:1
	ds_read2_b32 v[42:43], v58 offset1:1
	s_waitcnt lgkmcnt(4)
	v_pk_add_f32 v[32:33], v[32:33], v[44:45]
	v_fma_f32 v81, -v74, v75, 1.0
	s_waitcnt lgkmcnt(3)
	v_pk_add_f32 v[32:33], v[32:33], v[34:35]
	v_pk_add_f32 v[34:35], v[38:39], 0 op_sel_hi:[1,0]
	v_div_scale_f32 v80, vcc, 1.0, v71, 1.0
	v_fmac_f32_e32 v75, v81, v75
	s_waitcnt lgkmcnt(2)
	v_pk_add_f32 v[34:35], v[34:35], v[36:37]
	v_add_u32_e32 v59, 0x8208, v79
	v_mul_f32_e32 v81, v80, v75
	s_waitcnt lgkmcnt(1)
	v_pk_add_f32 v[34:35], v[34:35], v[40:41]
	v_add_u32_e32 v60, 0xa288, v79
	v_add_u32_e32 v61, 0xc308, v79
	v_add_u32_e32 v62, 0xe388, v79
	ds_read2_b32 v[36:37], v59 offset1:1
	ds_read2_b32 v[38:39], v60 offset1:1
	ds_read2_b32 v[40:41], v61 offset1:1
	ds_read2_b32 v[44:45], v62 offset1:1
	v_fma_f32 v82, -v74, v81, v80
	s_waitcnt lgkmcnt(4)
	v_pk_add_f32 v[34:35], v[34:35], v[42:43]
	v_fmac_f32_e32 v81, v82, v75
	s_waitcnt lgkmcnt(3)
	v_pk_add_f32 v[34:35], v[34:35], v[36:37]
	v_fma_f32 v74, -v74, v81, v80
	s_waitcnt lgkmcnt(2)
	v_pk_add_f32 v[34:35], v[34:35], v[38:39]
	v_div_fmas_f32 v74, v74, v75, v81
	s_ashr_i32 s14, s6, 6
	s_waitcnt lgkmcnt(1)
	v_pk_add_f32 v[34:35], v[34:35], v[40:41]
	s_waitcnt lgkmcnt(0)
	s_barrier
	v_div_fixup_f32 v74, v74, v71, 1.0
	s_waitcnt lgkmcnt(0)
	v_pk_add_f32 v[34:35], v[34:35], v[44:45]
	s_cmp_lt_i32 s14, 2
	v_pk_mul_f32 v[32:33], v[74:75], v[32:33] op_sel_hi:[0,1]
	v_pk_mul_f32 v[34:35], v[74:75], v[34:35] op_sel_hi:[0,1]
	s_cselect_b64 s[10:11], -1, 0
	s_cmp_gt_i32 s14, 1
	v_lshlrev_b32_e32 v43, 2, v146
	s_cbranch_scc1 .LBB0_1835
	v_mov_b32_e32 v38, v33
	v_mov_b32_e32 v39, v35
	v_mov_b32_e32 v36, v32
	v_mov_b32_e32 v37, v34
	v_pk_mul_f32 v[38:39], v[38:39], v[38:39]
	s_cmp_lt_u32 s15, 16
	v_pk_fma_f32 v[36:37], v[36:37], v[36:37], v[38:39]
	s_nop 0
	v_add_f32_e32 v36, v36, v37
	ds_swizzle_b32 v37, v36 offset:swizzle(SWAP,1)
	s_waitcnt lgkmcnt(0)
	v_add_f32_e32 v36, v36, v37
	ds_swizzle_b32 v37, v36 offset:swizzle(SWAP,2)
	s_waitcnt lgkmcnt(0)
	v_add_f32_e32 v36, v36, v37
	ds_swizzle_b32 v37, v36 offset:swizzle(SWAP,4)
	s_waitcnt lgkmcnt(0)
	v_add_f32_e32 v36, v36, v37
	ds_swizzle_b32 v37, v36 offset:swizzle(SWAP,8)
	s_waitcnt lgkmcnt(0)
	v_add_f32_e32 v36, v36, v37
	v_fmamk_f32 v36, v36, 0x3c800000, v242
	v_cmp_gt_f32_e32 vcc, s19, v36
	v_mul_f32_e32 v37, 0x4f800000, v36
	s_nop 0
	v_cndmask_b32_e32 v36, v36, v37, vcc
	v_sqrt_f32_e32 v37, v36
	s_nop 0
	v_add_u32_e32 v38, -1, v37
	v_fma_f32 v39, -v38, v37, v36
	v_cmp_ge_f32_e64 s[40:41], 0, v39
	v_add_u32_e32 v39, 1, v37
	s_nop 0
	v_cndmask_b32_e64 v38, v37, v38, s[40:41]
	v_fma_f32 v37, -v39, v37, v36
	v_cmp_lt_f32_e64 s[40:41], 0, v37
	s_nop 1
	v_cndmask_b32_e64 v37, v38, v39, s[40:41]
	v_mul_f32_e32 v38, 0x37800000, v37
	v_cndmask_b32_e32 v37, v37, v38, vcc
	v_cmp_class_f32_e32 vcc, v36, v243
	s_nop 1
	v_cndmask_b32_e32 v36, v37, v36, vcc
	v_div_scale_f32 v37, s[12:13], v36, v36, 1.0
	s_cselect_b32 s13, s73, s86
	s_cselect_b32 s12, s72, s85
	v_rcp_f32_e32 v38, v37
	s_nop 1
	global_load_dwordx4 v[80:83], v43, s[12:13]
	v_fma_f32 v39, -v37, v38, 1.0
	v_fmac_f32_e32 v38, v39, v38
	v_div_scale_f32 v39, vcc, 1.0, v36, 1.0
	v_mul_f32_e32 v40, v39, v38
	v_fma_f32 v41, -v37, v40, v39
	v_fmac_f32_e32 v40, v41, v38
	v_fma_f32 v37, -v37, v40, v39
	v_div_fmas_f32 v37, v37, v38, v40
	v_div_fixup_f32 v42, v37, v36, 1.0
	s_waitcnt vmcnt(0)
	v_mul_f32_e32 v36, v82, v42
	v_mul_f32_e32 v45, v34, v36
	v_mul_f32_e32 v34, v83, v42
	v_mul_f32_e32 v44, v35, v34
	global_load_dwordx4 v[34:37], v[68:69], off
	global_load_dwordx4 v[38:41], v[68:69], off offset:128
	v_pk_mul_f32 v[80:81], v[80:81], v[42:43] op_sel_hi:[1,0]
	ds_swizzle_b32 v63, v45 offset:swizzle(SWAP,8)
	v_pk_mul_f32 v[32:33], v[32:33], v[80:81]
	ds_swizzle_b32 v42, v32 offset:swizzle(SWAP,8)
	ds_swizzle_b32 v75, v33 offset:swizzle(SWAP,8)
	ds_swizzle_b32 v71, v44 offset:swizzle(SWAP,8)
	s_waitcnt lgkmcnt(2)
	v_cndmask_b32_e64 v80, v42, -v42, s[38:39]
	s_waitcnt lgkmcnt(1)
	v_cndmask_b32_e64 v81, v75, -v75, s[38:39]
	v_cndmask_b32_e64 v42, v63, -v63, s[38:39]
	s_waitcnt vmcnt(1)
	v_mul_f32_e32 v36, v36, v45
	s_waitcnt vmcnt(0)
	v_pk_mul_f32 v[38:39], v[80:81], v[38:39]
	v_mul_f32_e32 v80, v42, v40
	s_waitcnt lgkmcnt(0)
	v_cndmask_b32_e64 v45, v71, -v71, s[38:39]
	v_mov_b32_e32 v40, v37
	v_pk_mul_f32 v[40:41], v[40:41], v[44:45]
	v_pk_fma_f32 v[32:33], v[34:35], v[32:33], v[38:39]
	v_mov_b32_e32 v37, v40
	v_mov_b32_e32 v81, v41
	v_pk_add_f32 v[34:35], v[36:37], v[80:81]

.LBB0_2168:
	s_load_dwordx2 s[10:11], s[0:1], 0x118
	v_readlane_b32 s6, v255, 27
	v_readlane_b32 s7, v255, 28
	v_and_b32_e32 v147, 15, v146
	v_lshlrev_b32_e32 v144, 2, v147
	s_waitcnt lgkmcnt(0)
	s_add_u32 s0, s10, 0xec00000
	s_addc_u32 s1, s11, 0
	s_add_u32 s2, s10, 0x210000
	s_addc_u32 s3, s11, 0
	s_and_b64 s[6:7], s[6:7], exec
	s_cselect_b32 s6, 0x200000, 0
	s_add_u32 s6, s10, s6
	s_addc_u32 s7, s11, 0
	s_add_u32 s12, s6, 0x1800000
	s_addc_u32 s13, s7, 0
	s_andn2_b64 vcc, exec, s[14:15]
	s_cbranch_vccnz .LBB0_2210
	v_bfe_i32 v2, v145, 27, 1
	v_lshlrev_b32_e32 v0, 4, v145
	v_lshrrev_b32_e32 v2, 22, v2
	v_add_u32_e32 v2, v0, v2
	v_and_b32_e32 v2, 0xfffffc00, v2
	v_sub_u32_e32 v2, v0, v2
	v_ashrrev_i32_e32 v1, 31, v145
	v_lshrrev_b32_e32 v3, 4, v2
	v_lshrrev_b32_e32 v1, 26, v1
	v_bitop3_b32 v2, v3, v2, 32 bitop3:0x6c
	v_add_u32_e32 v1, v145, v1
	v_ashrrev_i32_e32 v4, 31, v2
	v_ashrrev_i32_e32 v1, 6, v1
	v_lshrrev_b32_e32 v4, 26, v4
	v_lshlrev_b32_e32 v3, 3, v1
	v_add_u32_e32 v4, v2, v4
	v_and_b32_e32 v3, -16, v3
	v_ashrrev_i32_e32 v5, 6, v4
	v_lshlrev_b32_e32 v1, 5, v1
	v_add_u32_e32 v3, v5, v3
	v_and_b32_e32 v12, 32, v1
	v_and_b32_e32 v1, 0xc0, v4
	v_sub_u32_e32 v1, v2, v1
	v_mov_b32_e32 v6, 1
	v_lshlrev_b32_e32 v2, 1, v3
	v_lshrrev_b32_e32 v4, 2, v3
	v_and_b32_e32 v5, 3, v5
	s_mov_b32 s14, 0x7fffffe0
	v_ashrrev_i16_sdwa v1, v6, sext(v1) dst_sel:DWORD dst_unused:UNUSED_PAD src0_sel:DWORD src1_sel:BYTE_0
	v_and_b32_e32 v2, 24, v2
	v_and_b32_e32 v4, 4, v4
	v_and_or_b32 v5, v3, s14, v5
	v_bfe_i32 v13, v1, 0, 16
	v_or3_b32 v2, v5, v4, v2
	v_add_u32_e32 v1, v12, v13
	v_mul_lo_u32 v14, v3, s26
	v_mul_lo_u32 v2, v2, s26
	v_add_u32_e32 v0, 0x2000, v0
	v_add_lshl_u32 v130, v1, v14, 1
	v_add_lshl_u32 v132, v2, v1, 1
	v_ashrrev_i32_e32 v1, 31, v0
	v_lshrrev_b32_e32 v1, 22, v1
	v_add_u32_e32 v1, v0, v1
	v_ashrrev_i32_e32 v1, 10, v1
	s_add_u32 s6, s10, 0x1ee00000
	v_mul_i32_i24_e32 v2, 0x400, v1
	s_addc_u32 s7, s11, 0
	v_sub_u32_e32 v0, v0, v2
	s_ashr_i32 s27, s26, 31
	v_lshrrev_b32_e32 v2, 4, v0
	s_lshl_b64 s[22:23], s[26:27], 9
	s_ashr_i32 s20, s65, 31
	v_bitop3_b32 v0, v2, v0, 32 bitop3:0x6c
	s_mul_i32 s20, s22, s20
	s_mul_hi_u32 s24, s22, s65
	v_ashrrev_i32_e32 v3, 31, v0
	s_add_i32 s20, s24, s20
	s_lshr_b64 s[24:25], s[26:27], 23
	v_lshrrev_b32_e32 v3, 26, v3
	s_mul_i32 s25, s24, s65
	v_lshlrev_b32_e32 v2, 3, v1
	v_add_u32_e32 v3, v0, v3
	s_add_i32 s38, s20, s25
	s_ashr_i32 s20, s62, 31
	v_and_b32_e32 v2, -16, v2
	v_ashrrev_i32_e32 v4, 6, v3
	s_mul_i32 s20, s22, s20
	s_mul_hi_u32 s25, s22, s62
	s_ashr_i32 s36, s33, 6
	v_add_u32_e32 v2, v4, v2
	v_lshlrev_b32_e32 v1, 5, v1
	v_and_b32_e32 v4, 3, v4
	s_add_i32 s20, s25, s20
	s_mul_i32 s24, s24, s62
	v_and_b32_e32 v15, 32, v1
	v_and_b32_e32 v1, 0xc0, v3
	v_and_or_b32 v4, v2, s14, v4
	s_ashr_i32 s37, s33, 8
	s_lshl_b64 s[14:15], s[26:27], 8
	s_lshl_b32 s18, s36, 10
	s_add_i32 s20, s20, s24
	s_mul_i32 s24, s22, s62
	v_sub_u32_e32 v0, v0, v1
	v_lshlrev_b32_e32 v1, 1, v2
	v_lshrrev_b32_e32 v3, 2, v2
	s_add_u32 s28, s12, s24
	v_ashrrev_i16_sdwa v0, v6, sext(v0) dst_sel:DWORD dst_unused:UNUSED_PAD src0_sel:DWORD src1_sel:BYTE_0
	v_and_b32_e32 v1, 24, v1
	v_and_b32_e32 v3, 4, v3
	s_addc_u32 s29, s13, s20
	s_add_i32 s20, s18, 0
	v_bfe_i32 v16, v0, 0, 16
	v_or3_b32 v1, v4, v3, v1
	s_add_i32 m0, s20, 0x10000
	v_add_u32_e32 v0, v15, v16
	v_mul_lo_u32 v1, v1, s26
	global_load_lds_dwordx4 v132, s[28:29]
	s_add_i32 m0, s20, 0x12000
	v_add_lshl_u32 v136, v1, v0, 1
	s_add_u32 s24, s28, s14
	global_load_lds_dwordx4 v136, s[28:29]
	s_addc_u32 s25, s29, s15
	s_add_i32 m0, s20, 0x14000
	s_mul_i32 s39, s22, s65
	global_load_lds_dwordx4 v132, s[24:25]
	s_add_i32 m0, s20, 0x16000
	s_add_u32 s46, s6, s39
	v_mov_b32_e32 v133, v129
	v_mov_b32_e32 v137, v129
	s_addc_u32 s47, s7, s38
	s_add_i32 s48, s20, 0x2000
	v_mul_lo_u32 v17, v2, s26
	v_lshl_add_u64 v[4:5], s[24:25], 0, v[132:133]
	v_lshl_add_u64 v[6:7], s[24:25], 0, v[136:137]
	global_load_lds_dwordx4 v136, s[24:25]
	s_mov_b32 m0, s20
	s_add_u32 s24, s46, s14
	v_add_lshl_u32 v134, v0, v17, 1
	global_load_lds_dwordx4 v130, s[46:47]
	s_mov_b32 m0, s48
	s_addc_u32 s25, s47, s15
	s_add_i32 s49, s20, 0x4000
	global_load_lds_dwordx4 v134, s[46:47]
	s_mov_b32 m0, s49
	s_add_i32 s50, s20, 0x6000
	global_load_lds_dwordx4 v130, s[24:25]
	s_mov_b32 m0, s50
	v_mov_b32_e32 v131, v129
	global_load_lds_dwordx4 v134, s[24:25]
	v_mov_b32_e32 v135, v129
	s_cmp_eq_u32 s37, 1
	v_lshl_add_u64 v[0:1], s[28:29], 0, v[132:133]
	v_lshl_add_u64 v[2:3], s[28:29], 0, v[136:137]
	v_lshl_add_u64 v[8:9], s[46:47], 0, v[130:131]
	v_lshl_add_u64 v[10:11], s[46:47], 0, v[134:135]
	s_cselect_b64 s[24:25], -1, 0
	s_add_i32 m0, s20, 0x18000
	v_lshl_add_u64 v[0:1], v[0:1], 0, s[34:35]
	global_load_lds_dwordx4 v[0:1], off
	v_lshl_add_u64 v[0:1], v[2:3], 0, s[34:35]
	s_add_i32 m0, s20, 0x1a000
	s_add_i32 s51, s20, 0x8000
	global_load_lds_dwordx4 v[0:1], off
	v_lshl_add_u64 v[0:1], v[8:9], 0, s[34:35]
	s_mov_b32 m0, s51
	s_add_i32 s52, s20, 0xa000
	global_load_lds_dwordx4 v[0:1], off
	v_lshl_add_u64 v[0:1], v[10:11], 0, s[34:35]
	s_mov_b32 m0, s52
	s_lshr_b32 s27, s27, 26
	global_load_lds_dwordx4 v[0:1], off
	s_add_i32 m0, s20, 0x1c000
	v_lshl_add_u64 v[0:1], v[4:5], 0, s[34:35]
	global_load_lds_dwordx4 v[0:1], off
	v_lshl_add_u64 v[0:1], v[6:7], 0, s[34:35]
	s_add_i32 m0, s20, 0x1e000
	s_add_i32 s27, s26, s27
	global_load_lds_dwordx4 v[0:1], off
	s_cmp_lg_u32 s37, 1
	s_cbranch_scc1 .Lpro_6
	s_barrier

.LBB0_2302:
	s_waitcnt vmcnt(3)
	v_bfe_i32 v2, v131, 27, 1
	v_lshlrev_b32_e32 v0, 4, v131
	v_lshrrev_b32_e32 v2, 22, v2
	v_add_u32_e32 v2, v0, v2
	v_and_b32_e32 v2, 0xfffffc00, v2
	v_sub_u32_e32 v2, v0, v2
	v_ashrrev_i32_e32 v1, 31, v131
	v_lshrrev_b32_e32 v3, 4, v2
	v_lshrrev_b32_e32 v1, 26, v1
	v_bitop3_b32 v2, v3, v2, 32 bitop3:0x6c
	v_add_u32_e32 v1, v131, v1
	s_waitcnt vmcnt(2)
	v_ashrrev_i32_e32 v4, 31, v2
	v_ashrrev_i32_e32 v1, 6, v1
	v_lshrrev_b32_e32 v4, 26, v4
	v_lshlrev_b32_e32 v3, 3, v1
	v_add_u32_e32 v4, v2, v4
	v_and_b32_e32 v3, -16, v3
	v_ashrrev_i32_e32 v5, 6, v4
	v_lshlrev_b32_e32 v1, 5, v1
	v_add_u32_e32 v3, v5, v3
	s_waitcnt vmcnt(0)
	v_and_b32_e32 v12, 32, v1
	v_and_b32_e32 v1, 0xc0, v4
	v_sub_u32_e32 v1, v2, v1
	v_mov_b32_e32 v6, 1
	v_lshlrev_b32_e32 v2, 1, v3
	v_lshrrev_b32_e32 v4, 2, v3
	v_and_b32_e32 v5, 3, v5
	s_mov_b32 s6, 0x7fffffe0
	v_ashrrev_i16_sdwa v1, v6, sext(v1) dst_sel:DWORD dst_unused:UNUSED_PAD src0_sel:DWORD src1_sel:BYTE_0
	v_and_b32_e32 v2, 24, v2
	v_and_b32_e32 v4, 4, v4
	v_and_or_b32 v5, v3, s6, v5
	v_bfe_i32 v13, v1, 0, 16
	v_or3_b32 v2, v5, v4, v2
	v_add_u32_e32 v1, v12, v13
	v_mul_lo_u32 v14, s36, v3
	v_mul_lo_u32 v2, s36, v2
	v_add_u32_e32 v0, 0x2000, v0
	v_add_lshl_u32 v132, v14, v1, 1
	v_add_lshl_u32 v128, v2, v1, 1
	v_ashrrev_i32_e32 v1, 31, v0
	v_lshrrev_b32_e32 v1, 22, v1
	v_add_u32_e32 v1, v0, v1
	v_ashrrev_i32_e32 v1, 10, v1
	v_mul_i32_i24_e32 v2, 0x400, v1
	v_sub_u32_e32 v0, v0, v2
	v_lshrrev_b32_e32 v2, 4, v0
	v_bitop3_b32 v0, v2, v0, 32 bitop3:0x6c
	v_ashrrev_i32_e32 v3, 31, v0
	v_lshrrev_b32_e32 v3, 26, v3
	v_lshlrev_b32_e32 v2, 3, v1
	v_add_u32_e32 v3, v0, v3
	v_and_b32_e32 v2, -16, v2
	v_ashrrev_i32_e32 v4, 6, v3
	v_add_u32_e32 v2, v4, v2
	v_and_b32_e32 v4, 3, v4
	s_ashr_i32 s39, s33, 6
	s_ashr_i32 s37, s36, 31
	s_ashr_i32 s38, s33, 8
	v_and_or_b32 v4, v2, s6, v4
	s_lshl_b64 s[22:23], s[36:37], 8
	s_lshl_b64 s[24:25], s[36:37], 9
	s_lshl_b32 s6, s39, 10
	s_add_u32 s7, s2, 0xec00000
	s_addc_u32 s18, s3, 0
	s_add_i32 s20, s20, s26
	s_ashr_i32 s26, s20, 31
	s_lshr_b32 s26, s26, 25
	s_add_i32 s26, s20, s26
	s_ashr_i32 s27, s26, 7
	s_and_b32 s26, s26, 0xff80
	s_sub_i32 s26, s20, s26
	s_bfe_i32 s20, s26, 0x80000
	s_bfe_u32 s20, s20, 0x3000c
	s_add_i32 s28, s26, s20
	s_bfe_i32 s20, s28, 0x80000
	s_and_b32 s28, s28, 0xf8
	s_sub_i32 s26, s26, s28
	s_lshl_b32 s27, s27, 3
	s_sext_i32_i8 s26, s26
	s_add_i32 s60, s27, s26
	s_ashr_i32 s26, s60, 31
	s_mul_i32 s26, s24, s26
	s_mul_hi_u32 s27, s24, s60
	s_sext_i32_i16 s40, s20
	s_add_i32 s28, s27, s26
	s_lshr_b64 s[26:27], s[36:37], 23
	s_lshr_b32 s20, s40, 3
	s_mul_i32 s27, s26, s60
	s_add_i32 s41, s28, s27
	s_bfe_i64 s[28:29], s[20:21], 0x100000
	s_ashr_i32 s27, s40, 3
	s_mul_hi_u32 s28, s24, s27
	s_mul_i32 s29, s24, s29
	v_lshlrev_b32_e32 v1, 5, v1
	s_add_i32 s28, s28, s29
	s_mul_i32 s26, s26, s27
	v_and_b32_e32 v15, 32, v1
	v_and_b32_e32 v1, 0xc0, v3
	s_add_i32 s26, s28, s26
	s_mul_i32 s27, s24, s27
	v_sub_u32_e32 v0, v0, v1
	v_lshlrev_b32_e32 v1, 1, v2
	v_lshrrev_b32_e32 v3, 2, v2
	s_add_u32 s28, s14, s27
	v_ashrrev_i16_sdwa v0, v6, sext(v0) dst_sel:DWORD dst_unused:UNUSED_PAD src0_sel:DWORD src1_sel:BYTE_0
	v_and_b32_e32 v1, 24, v1
	v_and_b32_e32 v3, 4, v3
	s_addc_u32 s29, s15, s26
	s_add_i32 s48, s6, 0
	v_bfe_i32 v16, v0, 0, 16
	v_or3_b32 v1, v4, v3, v1
	s_add_i32 m0, s48, 0x10000
	v_add_u32_e32 v0, v15, v16
	v_mul_lo_u32 v1, s36, v1
	global_load_lds_dwordx4 v128, s[28:29]
	s_add_i32 m0, s48, 0x12000
	v_add_lshl_u32 v136, v1, v0, 1
	s_add_u32 s26, s28, s22
	global_load_lds_dwordx4 v136, s[28:29]
	s_addc_u32 s27, s29, s23
	s_add_i32 m0, s48, 0x14000
	s_mul_i32 s42, s24, s60
	global_load_lds_dwordx4 v128, s[26:27]
	s_add_i32 m0, s48, 0x16000
	s_add_u32 s46, s7, s42
	v_mov_b32_e32 v137, v129
	s_addc_u32 s47, s18, s41
	s_add_i32 s49, s48, 0x2000
	v_mul_lo_u32 v17, s36, v2
	v_lshl_add_u64 v[4:5], s[26:27], 0, v[128:129]
	v_lshl_add_u64 v[6:7], s[26:27], 0, v[136:137]
	global_load_lds_dwordx4 v136, s[26:27]
	s_mov_b32 m0, s48
	s_add_u32 s26, s46, s22
	v_add_lshl_u32 v134, v17, v0, 1
	global_load_lds_dwordx4 v132, s[46:47]
	s_mov_b32 m0, s49
	s_addc_u32 s27, s47, s23
	s_add_i32 s50, s48, 0x4000
	global_load_lds_dwordx4 v134, s[46:47]
	s_mov_b32 m0, s50
	s_add_i32 s51, s48, 0x6000
	global_load_lds_dwordx4 v132, s[26:27]
	s_mov_b32 m0, s51
	v_mov_b32_e32 v133, v129
	global_load_lds_dwordx4 v134, s[26:27]
	v_mov_b32_e32 v135, v129
	s_cmp_eq_u32 s38, 1
	v_lshl_add_u64 v[0:1], s[28:29], 0, v[128:129]
	v_lshl_add_u64 v[2:3], s[28:29], 0, v[136:137]
	v_lshl_add_u64 v[8:9], s[46:47], 0, v[132:133]
	v_lshl_add_u64 v[10:11], s[46:47], 0, v[134:135]
	s_cselect_b64 s[26:27], -1, 0
	s_add_i32 m0, s48, 0x18000
	v_lshl_add_u64 v[0:1], v[0:1], 0, s[34:35]
	global_load_lds_dwordx4 v[0:1], off
	v_lshl_add_u64 v[0:1], v[2:3], 0, s[34:35]
	s_add_i32 m0, s48, 0x1a000
	s_add_i32 s52, s48, 0x8000
	global_load_lds_dwordx4 v[0:1], off
	v_lshl_add_u64 v[0:1], v[8:9], 0, s[34:35]
	s_mov_b32 m0, s52
	s_add_i32 s53, s48, 0xa000
	global_load_lds_dwordx4 v[0:1], off
	v_lshl_add_u64 v[0:1], v[10:11], 0, s[34:35]
	s_mov_b32 m0, s53
	s_sext_i32_i8 s61, s20
	global_load_lds_dwordx4 v[0:1], off
	s_add_i32 m0, s48, 0x1c000
	v_lshl_add_u64 v[0:1], v[4:5], 0, s[34:35]
	global_load_lds_dwordx4 v[0:1], off
	v_lshl_add_u64 v[0:1], v[6:7], 0, s[34:35]
	s_add_i32 m0, s48, 0x1e000
	s_lshr_b32 s20, s37, 26
	global_load_lds_dwordx4 v[0:1], off
	s_cmp_lg_u32 s38, 1
	s_cbranch_scc1 .Lpro_7
	s_barrier
.Lpro_7:
	s_waitcnt vmcnt(8)
	s_barrier
	v_lshrrev_b32_e32 v0, 1, v150
	v_and_b32_e32 v0, 24, v0
	v_lshlrev_b32_e32 v1, 1, v0
	v_lshl_or_b32 v1, v151, 6, v1
	s_lshl_b32 s37, s38, 13
	v_and_b32_e32 v2, 32, v130
	v_bitop3_b32 v3, v1, s37, v2 bitop3:0xde
	s_lshl_b32 s37, s39, 5
	s_add_i32 s20, s36, s20
	s_and_b32 s39, s37, 0x60
	s_ashr_i32 s20, s20, 6
	s_lshl_b32 s37, s39, 7
	s_cmp_gt_i32 s36, 63
	v_bitop3_b32 v153, s37, v1, v2 bitop3:0xf6
	s_cselect_b64 s[36:37], -1, 0
	s_add_i32 s56, s20, -2
	s_cmpk_lt_u32 s33, 0x100
	v_or_b32_e32 v159, s39, v0
	v_add_u32_e32 v0, v14, v12
	s_cselect_b64 s[42:43], -1, 0
	s_lshl_b32 s33, s38, 8
	v_add_lshl_u32 v0, v0, v13, 1
	v_mov_b32_e32 v1, v129
	s_waitcnt vmcnt(6)
	s_add_i32 s33, s33, 0
	v_lshl_add_u64 v[138:139], s[22:23], 0, v[0:1]
	v_add_u32_e32 v0, v17, v15
	v_lshl_or_b32 v152, s38, 6, v151
	s_add_i32 s33, s33, 0x20800
	v_add_lshl_u32 v0, v0, v16, 1
	v_add_u32_e32 v154, 0x80, v152
	v_add_u32_e32 v155, 0x90, v152
	v_add_u32_e32 v156, 0xa0, v152
	v_add_u32_e32 v157, 0xb0, v152
	v_add_u32_e32 v158, s33, v130
	v_lshl_add_u64 v[140:141], s[22:23], 0, v[0:1]
	s_mov_b32 s62, 0
	v_add_u32_e32 v160, 0, v3
	s_barrier
	s_branch .LBB0_2307

.LBB0_2331:
	s_and_b32 s10, s14, 0xffffff80
	v_or_b32_e32 v0, s10, v72
	v_ashrrev_i32_e32 v1, 31, v0
	s_and_b32 s11, s14, 0xffffffc0
	v_lshlrev_b64 v[16:17], 11, v[0:1]
	v_or_b32_e32 v0, 32, v0
	v_ashrrev_i32_e32 v1, 31, v0
	s_or_b32 s2, s11, 64
	v_lshlrev_b64 v[18:19], 11, v[0:1]
	v_or_b32_e32 v0, s2, v72
	s_and_b32 s3, s7, 0xe0
	v_ashrrev_i32_e32 v1, 31, v0
	v_lshlrev_b64 v[20:21], 11, v[0:1]
	v_or_b32_e32 v0, s11, v75
	v_add_u32_e32 v70, s3, v73
	v_ashrrev_i32_e32 v1, 31, v0
	v_ashrrev_i32_e32 v71, 31, v70
	v_lshlrev_b64 v[22:23], 11, v[0:1]
	v_lshlrev_b64 v[0:1], 6, v[70:71]
	v_lshl_add_u64 v[12:13], s[0:1], 0, v[0:1]
	global_load_dwordx4 v[32:35], v[12:13], off offset:32
	global_load_dwordx4 v[36:39], v[12:13], off offset:48
	global_load_dwordx4 v[40:43], v[12:13], off
	s_nop 0
	global_load_dwordx4 v[44:47], v[12:13], off offset:16
	v_or_b32_e32 v24, s3, v72
	v_lshlrev_b32_e32 v128, 11, v24
	v_lshl_add_u64 v[126:127], v[64:65], 0, v[128:129]
	v_lshl_add_u64 v[142:143], v[66:67], 0, v[16:17]
	v_lshl_add_u64 v[144:145], v[66:67], 0, v[18:19]
	v_lshl_add_u64 v[150:151], v[66:67], 0, v[20:21]
	v_lshl_add_u64 v[158:159], v[66:67], 0, v[22:23]
	global_load_dwordx4 v[16:19], v[126:127], off
	global_load_dwordx4 v[0:3], v[142:143], off
	global_load_dwordx4 v[4:7], v[144:145], off
	global_load_dwordx4 v[8:11], v[150:151], off
	global_load_dwordx4 v[20:23], v[158:159], off
	global_load_dwordx4 v[78:81], v[126:127], off offset:32
	global_load_dwordx4 v[82:85], v[142:143], off offset:32
	global_load_dwordx4 v[86:89], v[144:145], off offset:32
	global_load_dwordx4 v[90:93], v[150:151], off offset:32
	global_load_dwordx4 v[94:97], v[158:159], off offset:32
	global_load_dwordx4 v[98:101], v[126:127], off offset:64
	global_load_dwordx4 v[102:105], v[142:143], off offset:64
	global_load_dwordx4 v[106:109], v[144:145], off offset:64
	global_load_dwordx4 v[110:113], v[150:151], off offset:64
	global_load_dwordx4 v[114:117], v[158:159], off offset:64
	global_load_dwordx4 v[118:121], v[126:127], off offset:96
	global_load_dwordx4 v[122:125], v[142:143], off offset:96
	global_load_dwordx4 v[130:133], v[144:145], off offset:96
	global_load_dwordx4 v[134:137], v[150:151], off offset:96
	global_load_dwordx4 v[138:141], v[158:159], off offset:96
	s_waitcnt vmcnt(22)
	v_pk_add_f32 v[34:35], v[34:35], v[38:39]
	v_pk_add_f32 v[32:33], v[32:33], v[36:37]
	s_waitcnt vmcnt(20)
	v_pk_add_f32 v[42:43], v[42:43], v[46:47]
	v_pk_add_f32 v[40:41], v[40:41], v[44:45]
	v_pk_add_f32 v[34:35], v[42:43], v[34:35]
	v_pk_add_f32 v[32:33], v[40:41], v[32:33]
	s_nop 0
	v_pk_mov_b32 v[36:37], v[32:33], v[34:35] op_sel:[1,0]
	v_mov_b32_e32 v33, v35
	v_pk_add_f32 v[32:33], v[36:37], v[32:33]
	s_nop 0
	v_add_f32_e32 v32, v32, v33
	v_fmamk_f32 v32, v32, 0x3a800000, v242
	v_cmp_gt_f32_e32 vcc, s19, v32
	v_mul_f32_e32 v33, 0x4f800000, v32
	s_nop 0
	v_cndmask_b32_e32 v32, v32, v33, vcc
	v_sqrt_f32_e32 v33, v32
	s_nop 0
	v_add_u32_e32 v34, -1, v33
	v_fma_f32 v35, -v34, v33, v32
	v_cmp_ge_f32_e64 s[38:39], 0, v35
	v_add_u32_e32 v35, 1, v33
	s_nop 0
	v_cndmask_b32_e64 v34, v33, v34, s[38:39]
	v_fma_f32 v33, -v35, v33, v32
	v_cmp_lt_f32_e64 s[38:39], 0, v33
	s_nop 1
	v_cndmask_b32_e64 v33, v34, v35, s[38:39]
	v_mul_f32_e32 v34, 0x37800000, v33
	v_cndmask_b32_e32 v33, v33, v34, vcc
	v_cmp_class_f32_e32 vcc, v32, v243
	s_nop 1
	v_cndmask_b32_e32 v69, v33, v32, vcc
	s_waitcnt vmcnt(18)
	v_mfma_f32_32x32x16_bf16 v[32:47], v[16:19], v[0:3], 0
	s_waitcnt vmcnt(17)
	v_mfma_f32_32x32x16_bf16 v[48:63], v[16:19], v[4:7], 0
	s_waitcnt vmcnt(16)
	v_mfma_f32_32x32x16_bf16 v[0:15], v[16:19], v[8:11], 0
	s_waitcnt vmcnt(15)
	v_mfma_f32_32x32x16_bf16 v[16:31], v[16:19], v[20:23], 0
	s_waitcnt vmcnt(13)
	v_mfma_f32_32x32x16_bf16 v[32:47], v[78:81], v[82:85], v[32:47]
	s_waitcnt vmcnt(12)
	v_mfma_f32_32x32x16_bf16 v[48:63], v[78:81], v[86:89], v[48:63]
	s_waitcnt vmcnt(11)
	v_mfma_f32_32x32x16_bf16 v[0:15], v[78:81], v[90:93], v[0:15]
	s_waitcnt vmcnt(10)
	v_mfma_f32_32x32x16_bf16 v[16:31], v[78:81], v[94:97], v[16:31]
	s_waitcnt vmcnt(8)
	v_mfma_f32_32x32x16_bf16 v[32:47], v[98:101], v[102:105], v[32:47]
	s_waitcnt vmcnt(7)
	v_mfma_f32_32x32x16_bf16 v[48:63], v[98:101], v[106:109], v[48:63]
	s_waitcnt vmcnt(6)
	v_mfma_f32_32x32x16_bf16 v[0:15], v[98:101], v[110:113], v[0:15]
	s_waitcnt vmcnt(5)
	v_mfma_f32_32x32x16_bf16 v[16:31], v[98:101], v[114:117], v[16:31]
	s_waitcnt vmcnt(3)
	v_mfma_f32_32x32x16_bf16 v[32:47], v[118:121], v[122:125], v[32:47]
	s_waitcnt vmcnt(2)
	v_mfma_f32_32x32x16_bf16 v[48:63], v[118:121], v[130:133], v[48:63]
	s_waitcnt vmcnt(1)
	v_mfma_f32_32x32x16_bf16 v[0:15], v[118:121], v[134:137], v[0:15]
	s_waitcnt vmcnt(0)
	v_mfma_f32_32x32x16_bf16 v[16:31], v[118:121], v[138:141], v[16:31]
	global_load_dwordx4 v[78:81], v[126:127], off offset:128
	global_load_dwordx4 v[82:85], v[126:127], off offset:160
	global_load_dwordx4 v[86:89], v[142:143], off offset:128
	global_load_dwordx4 v[90:93], v[142:143], off offset:160
	global_load_dwordx4 v[94:97], v[144:145], off offset:128
	global_load_dwordx4 v[98:101], v[144:145], off offset:160
	global_load_dwordx4 v[102:105], v[150:151], off offset:128
	global_load_dwordx4 v[106:109], v[150:151], off offset:160
	global_load_dwordx4 v[110:113], v[158:159], off offset:128
	global_load_dwordx4 v[114:117], v[158:159], off offset:160
	global_load_dwordx4 v[118:121], v[126:127], off offset:192
	global_load_dwordx4 v[122:125], v[126:127], off offset:224
	global_load_dwordx4 v[130:133], v[142:143], off offset:192
	global_load_dwordx4 v[134:137], v[142:143], off offset:224
	global_load_dwordx4 v[138:141], v[144:145], off offset:192
	s_nop 0
	global_load_dwordx4 v[142:145], v[144:145], off offset:224
	s_nop 0
	global_load_dwordx4 v[146:149], v[150:151], off offset:192
	s_nop 0
	global_load_dwordx4 v[150:153], v[150:151], off offset:224
	s_nop 0
	global_load_dwordx4 v[154:157], v[158:159], off offset:192
	s_nop 0
	global_load_dwordx4 v[158:161], v[158:159], off offset:224
	s_waitcnt vmcnt(17)
	v_mfma_f32_32x32x16_bf16 v[32:47], v[78:81], v[86:89], v[32:47]
	s_waitcnt vmcnt(15)
	v_mfma_f32_32x32x16_bf16 v[48:63], v[78:81], v[94:97], v[48:63]
	s_waitcnt vmcnt(13)
	v_mfma_f32_32x32x16_bf16 v[0:15], v[78:81], v[102:105], v[0:15]
	s_waitcnt vmcnt(11)
	v_mfma_f32_32x32x16_bf16 v[16:31], v[78:81], v[110:113], v[16:31]
	v_mfma_f32_32x32x16_bf16 v[32:47], v[82:85], v[90:93], v[32:47]
	v_mfma_f32_32x32x16_bf16 v[48:63], v[82:85], v[98:101], v[48:63]
	v_mfma_f32_32x32x16_bf16 v[0:15], v[82:85], v[106:109], v[0:15]
	s_waitcnt vmcnt(10)
	v_mfma_f32_32x32x16_bf16 v[16:31], v[82:85], v[114:117], v[16:31]
	s_waitcnt vmcnt(7)
	v_mfma_f32_32x32x16_bf16 v[32:47], v[118:121], v[130:133], v[32:47]
	s_waitcnt vmcnt(5)
	v_mfma_f32_32x32x16_bf16 v[48:63], v[118:121], v[138:141], v[48:63]
	s_waitcnt vmcnt(3)
	v_mfma_f32_32x32x16_bf16 v[0:15], v[118:121], v[146:149], v[0:15]
	s_waitcnt vmcnt(1)
	v_mfma_f32_32x32x16_bf16 v[16:31], v[118:121], v[154:157], v[16:31]
	v_mfma_f32_32x32x16_bf16 v[32:47], v[122:125], v[134:137], v[32:47]
	v_mfma_f32_32x32x16_bf16 v[48:63], v[122:125], v[142:145], v[48:63]
	v_mfma_f32_32x32x16_bf16 v[0:15], v[122:125], v[150:153], v[0:15]
	s_waitcnt vmcnt(0)
	v_mfma_f32_32x32x16_bf16 v[16:31], v[122:125], v[158:161], v[16:31]
	s_nop 8
	ds_write2_b32 v74, v32, v48 offset1:32
	ds_write2_b32 v74, v33, v49 offset0:65 offset1:97
	ds_write2_b32 v74, v34, v50 offset0:130 offset1:162
	ds_write2_b32 v74, v35, v51 offset0:195 offset1:227
	v_add_u32_e32 v48, 0x800, v74
	v_add_u32_e32 v49, 0x1000, v74
	ds_write2_b32 v48, v36, v52 offset0:8 offset1:40
	ds_write2_b32 v48, v37, v53 offset0:73 offset1:105
	ds_write2_b32 v48, v38, v54 offset0:138 offset1:170
	ds_write2_b32 v48, v39, v55 offset0:203 offset1:235
	ds_write2_b32 v49, v40, v56 offset0:16 offset1:48
	ds_write2_b32 v49, v41, v57 offset0:81 offset1:113
	ds_write2_b32 v49, v42, v58 offset0:146 offset1:178
	ds_write2_b32 v49, v43, v59 offset0:211 offset1:243
	v_add_u32_e32 v40, 0x1800, v74
	ds_write2_b32 v40, v44, v60 offset0:24 offset1:56
	ds_write2_b32 v40, v45, v61 offset0:89 offset1:121
	ds_write2_b32 v40, v46, v62 offset0:154 offset1:186
	ds_write2_b32 v40, v47, v63 offset0:219 offset1:251
	s_waitcnt lgkmcnt(0)
	s_barrier
	ds_read2_b32 v[32:33], v76 offset1:1
	v_add_u32_e32 v41, 0x2080, v76
	v_add_u32_e32 v42, 0x2088, v76
	ds_read2_b32 v[34:35], v76 offset0:2 offset1:3
	ds_read2_b32 v[36:37], v41 offset1:1
	ds_read2_b32 v[38:39], v42 offset1:1
	v_add_u32_e32 v47, 0x4100, v76
	s_waitcnt lgkmcnt(3)
	v_add_f32_e32 v32, 0, v32
	v_add_f32_e32 v33, 0, v33
	s_waitcnt lgkmcnt(1)
	v_add_f32_e32 v43, v32, v36
	v_add_f32_e32 v44, v33, v37
	ds_read2_b32 v[32:33], v47 offset1:1
	v_add_f32_e32 v34, 0, v34
	v_add_f32_e32 v35, 0, v35
	v_add_u32_e32 v50, 0x4108, v76
	s_waitcnt lgkmcnt(1)
	v_add_f32_e32 v45, v34, v38
	v_add_f32_e32 v46, v35, v39
	v_add_u32_e32 v51, 0x6180, v76
	v_add_u32_e32 v52, 0x6188, v76
	ds_read2_b32 v[34:35], v50 offset1:1
	ds_read2_b32 v[36:37], v51 offset1:1
	ds_read2_b32 v[38:39], v52 offset1:1
	s_waitcnt lgkmcnt(3)
	v_add_f32_e32 v32, v43, v32
	v_add_f32_e32 v33, v44, v33
	v_add_u32_e32 v53, 0x8200, v76
	v_div_scale_f32 v77, s[22:23], v69, v69, 1.0
	s_waitcnt lgkmcnt(1)
	v_add_f32_e32 v43, v32, v36
	v_add_f32_e32 v44, v33, v37
	ds_read2_b32 v[32:33], v53 offset1:1
	v_rcp_f32_e32 v78, v77
	v_add_f32_e32 v34, v45, v34
	v_add_f32_e32 v35, v46, v35
	v_add_u32_e32 v54, 0x8208, v76
	s_waitcnt lgkmcnt(1)
	v_add_f32_e32 v45, v34, v38
	v_add_f32_e32 v46, v35, v39
	v_add_u32_e32 v55, 0xa280, v76
	v_add_u32_e32 v56, 0xa288, v76
	ds_read2_b32 v[34:35], v54 offset1:1
	ds_read2_b32 v[36:37], v55 offset1:1
	ds_read2_b32 v[38:39], v56 offset1:1
	v_fma_f32 v80, -v77, v78, 1.0
	s_waitcnt lgkmcnt(3)
	v_add_f32_e32 v32, v43, v32
	v_add_f32_e32 v33, v44, v33
	v_add_u32_e32 v57, 0xc300, v76
	v_div_scale_f32 v79, vcc, 1.0, v69, 1.0
	v_fmac_f32_e32 v78, v80, v78
	s_waitcnt lgkmcnt(2)
	v_add_f32_e32 v34, v45, v34
	v_add_f32_e32 v35, v46, v35
	s_waitcnt lgkmcnt(1)
	v_add_f32_e32 v43, v32, v36
	v_add_f32_e32 v44, v33, v37
	ds_read2_b32 v[32:33], v57 offset1:1
	v_add_u32_e32 v58, 0xc308, v76
	v_mul_f32_e32 v80, v79, v78
	s_waitcnt lgkmcnt(1)
	v_add_f32_e32 v45, v34, v38
	v_add_f32_e32 v46, v35, v39
	v_add_u32_e32 v59, 0xe380, v76
	v_add_u32_e32 v60, 0xe388, v76
	ds_read2_b32 v[34:35], v58 offset1:1
	ds_read2_b32 v[36:37], v59 offset1:1
	ds_read2_b32 v[38:39], v60 offset1:1
	v_fma_f32 v81, -v77, v80, v79
	v_fmac_f32_e32 v80, v81, v78
	v_fma_f32 v77, -v77, v80, v79
	v_div_fmas_f32 v77, v77, v78, v80
	s_waitcnt lgkmcnt(3)
	v_add_f32_e32 v32, v43, v32
	v_add_f32_e32 v33, v44, v33
	s_waitcnt lgkmcnt(2)
	v_add_f32_e32 v34, v45, v34
	v_add_f32_e32 v35, v46, v35
	v_div_fixup_f32 v77, v77, v69, 1.0
	s_waitcnt lgkmcnt(1)
	v_add_f32_e32 v32, v32, v36
	v_add_f32_e32 v33, v33, v37
	s_waitcnt lgkmcnt(0)
	v_add_f32_e32 v34, v34, v38
	v_add_f32_e32 v35, v35, v39
	v_mul_f32_e32 v32, v77, v32
	v_mul_f32_e32 v33, v77, v33
	v_mul_f32_e32 v34, v77, v34
	v_mul_f32_e32 v35, v77, v35
	v_max_f32_e32 v32, 0, v32
	v_max_f32_e32 v33, 0, v33
	v_max_f32_e32 v34, 0, v34
	v_max_f32_e32 v35, 0, v35
	v_pk_mul_f32 v[32:33], v[32:33], v[32:33]
	v_pk_mul_f32 v[34:35], v[34:35], v[34:35]
	v_cvt_pk_bf16_f32 v32, v32, v33
	v_cvt_pk_bf16_f32 v33, v34, v35
	v_lshlrev_b64 v[34:35], 13, v[70:71]
	v_lshl_add_u64 v[34:35], s[12:13], 0, v[34:35]
	s_ashr_i32 s11, s10, 31
	v_lshl_add_u64 v[36:37], s[10:11], 1, v[34:35]
	v_mov_b32_e32 v69, v129
	v_lshl_add_u64 v[36:37], v[36:37], 0, v[68:69]
	s_waitcnt lgkmcnt(0)
	s_barrier
	global_store_dwordx2 v[36:37], v[32:33], off
	ds_write2_b32 v74, v0, v16 offset1:32
	ds_write2_b32 v74, v1, v17 offset0:65 offset1:97
	ds_write2_b32 v74, v2, v18 offset0:130 offset1:162
	ds_write2_b32 v74, v3, v19 offset0:195 offset1:227
	ds_write2_b32 v48, v4, v20 offset0:8 offset1:40
	ds_write2_b32 v48, v5, v21 offset0:73 offset1:105
	ds_write2_b32 v48, v6, v22 offset0:138 offset1:170
	ds_write2_b32 v48, v7, v23 offset0:203 offset1:235
	ds_write2_b32 v49, v8, v24 offset0:16 offset1:48
	ds_write2_b32 v49, v9, v25 offset0:81 offset1:113
	ds_write2_b32 v49, v10, v26 offset0:146 offset1:178
	ds_write2_b32 v49, v11, v27 offset0:211 offset1:243
	ds_write2_b32 v40, v12, v28 offset0:24 offset1:56
	ds_write2_b32 v40, v13, v29 offset0:89 offset1:121
	ds_write2_b32 v40, v14, v30 offset0:154 offset1:186
	ds_write2_b32 v40, v15, v31 offset0:219 offset1:251
	s_waitcnt lgkmcnt(0)
	s_barrier
	ds_read2_b32 v[0:1], v76 offset1:1
	ds_read2_b32 v[2:3], v76 offset0:2 offset1:3
	ds_read2_b32 v[4:5], v41 offset1:1
	ds_read2_b32 v[6:7], v42 offset1:1
	s_ashr_i32 s3, s2, 31
	s_waitcnt lgkmcnt(3)
	v_add_f32_e32 v0, 0, v0
	v_add_f32_e32 v1, 0, v1
	s_waitcnt lgkmcnt(1)
	v_add_f32_e32 v8, v0, v4
	v_add_f32_e32 v9, v1, v5
	ds_read2_b32 v[0:1], v47 offset1:1
	v_add_f32_e32 v2, 0, v2
	v_add_f32_e32 v3, 0, v3
	s_waitcnt lgkmcnt(1)
	v_add_f32_e32 v10, v2, v6
	v_add_f32_e32 v11, v3, v7
	ds_read2_b32 v[2:3], v50 offset1:1
	ds_read2_b32 v[4:5], v51 offset1:1
	ds_read2_b32 v[6:7], v52 offset1:1
	s_waitcnt lgkmcnt(3)
	v_add_f32_e32 v0, v8, v0
	v_add_f32_e32 v1, v9, v1
	s_waitcnt lgkmcnt(2)
	v_add_f32_e32 v2, v10, v2
	s_waitcnt lgkmcnt(1)
	v_add_f32_e32 v8, v0, v4
	v_add_f32_e32 v9, v1, v5
	ds_read2_b32 v[0:1], v53 offset1:1
	v_add_f32_e32 v3, v11, v3
	s_waitcnt lgkmcnt(1)
	v_add_f32_e32 v10, v2, v6
	v_add_f32_e32 v11, v3, v7
	ds_read2_b32 v[2:3], v54 offset1:1
	ds_read2_b32 v[4:5], v55 offset1:1
	ds_read2_b32 v[6:7], v56 offset1:1
	s_waitcnt lgkmcnt(3)
	v_add_f32_e32 v0, v8, v0
	v_add_f32_e32 v1, v9, v1
	s_waitcnt lgkmcnt(2)
	v_add_f32_e32 v2, v10, v2
	v_add_f32_e32 v3, v11, v3
	s_waitcnt lgkmcnt(1)
	v_add_f32_e32 v8, v0, v4
	v_add_f32_e32 v9, v1, v5
	ds_read2_b32 v[0:1], v57 offset1:1
	s_waitcnt lgkmcnt(1)
	v_add_f32_e32 v10, v2, v6
	v_add_f32_e32 v11, v3, v7
	ds_read2_b32 v[2:3], v58 offset1:1
	ds_read2_b32 v[4:5], v59 offset1:1
	ds_read2_b32 v[6:7], v60 offset1:1
	s_waitcnt lgkmcnt(0)
	s_barrier
	s_waitcnt lgkmcnt(3)
	v_add_f32_e32 v0, v8, v0
	v_add_f32_e32 v1, v9, v1
	s_waitcnt lgkmcnt(2)
	v_add_f32_e32 v2, v10, v2
	v_add_f32_e32 v3, v11, v3
	s_waitcnt lgkmcnt(1)
	v_add_f32_e32 v0, v0, v4
	v_add_f32_e32 v1, v1, v5
	s_waitcnt lgkmcnt(0)
	v_add_f32_e32 v2, v2, v6
	v_add_f32_e32 v3, v3, v7
	v_mul_f32_e32 v0, v77, v0
	v_mul_f32_e32 v1, v77, v1
	v_mul_f32_e32 v2, v77, v2
	v_mul_f32_e32 v3, v77, v3
	v_max_f32_e32 v0, 0, v0
	v_max_f32_e32 v1, 0, v1
	v_max_f32_e32 v2, 0, v2
	v_max_f32_e32 v3, 0, v3
	v_pk_mul_f32 v[0:1], v[0:1], v[0:1]
	v_pk_mul_f32 v[2:3], v[2:3], v[2:3]
	v_cvt_pk_bf16_f32 v0, v0, v1
	v_cvt_pk_bf16_f32 v1, v2, v3
	v_lshl_add_u64 v[2:3], s[2:3], 1, v[34:35]
	s_add_i32 s15, s15, s4
	s_add_i32 s14, s14, s5
	s_add_i32 s7, s7, s6
	v_lshl_add_u64 v[2:3], v[2:3], 0, v[68:69]
	s_cmpk_lt_i32 s15, 0x100
	global_store_dwordx2 v[2:3], v[0:1], off
	s_cbranch_scc1 .LBB0_2331

.LBB0_2389:
	s_load_dwordx2 s[10:11], s[0:1], 0x118
	v_readlane_b32 s6, v254, 60
	v_and_b32_e32 v147, 15, v146
	v_lshlrev_b32_e32 v144, 2, v147
	s_waitcnt lgkmcnt(0)
	s_add_u32 s0, s10, 0xec00000
	s_addc_u32 s1, s11, 0
	s_add_u32 s2, s10, 0x414000
	s_addc_u32 s3, s11, 0
	s_lshl_b32 s6, s6, 23
	s_add_u32 s6, s10, s6
	s_addc_u32 s7, s11, 0
	s_add_u32 s12, s6, 0x4b00000
	s_addc_u32 s13, s7, 0
	s_andn2_b64 vcc, exec, s[14:15]
	s_cbranch_vccnz .LBB0_2431
	v_bfe_i32 v2, v145, 27, 1
	v_lshlrev_b32_e32 v0, 4, v145
	v_lshrrev_b32_e32 v2, 22, v2
	v_add_u32_e32 v2, v0, v2
	v_and_b32_e32 v2, 0xfffffc00, v2
	v_sub_u32_e32 v2, v0, v2
	v_ashrrev_i32_e32 v1, 31, v145
	v_lshrrev_b32_e32 v3, 4, v2
	v_lshrrev_b32_e32 v1, 26, v1
	v_bitop3_b32 v2, v3, v2, 32 bitop3:0x6c
	v_add_u32_e32 v1, v145, v1
	v_ashrrev_i32_e32 v4, 31, v2
	v_ashrrev_i32_e32 v1, 6, v1
	v_lshrrev_b32_e32 v4, 26, v4
	v_lshlrev_b32_e32 v3, 3, v1
	v_add_u32_e32 v4, v2, v4
	v_and_b32_e32 v3, -16, v3
	v_ashrrev_i32_e32 v5, 6, v4
	v_lshlrev_b32_e32 v1, 5, v1
	v_add_u32_e32 v3, v5, v3
	v_and_b32_e32 v12, 32, v1
	v_and_b32_e32 v1, 0xc0, v4
	v_sub_u32_e32 v1, v2, v1
	v_mov_b32_e32 v6, 1
	v_lshlrev_b32_e32 v2, 1, v3
	v_lshrrev_b32_e32 v4, 2, v3
	v_and_b32_e32 v5, 3, v5
	s_mov_b32 s14, 0x7fffffe0
	v_ashrrev_i16_sdwa v1, v6, sext(v1) dst_sel:DWORD dst_unused:UNUSED_PAD src0_sel:DWORD src1_sel:BYTE_0
	v_and_b32_e32 v2, 24, v2
	v_and_b32_e32 v4, 4, v4
	v_and_or_b32 v5, v3, s14, v5
	v_bfe_i32 v13, v1, 0, 16
	v_or3_b32 v2, v5, v4, v2
	v_add_u32_e32 v1, v12, v13
	v_mul_lo_u32 v14, v3, s26
	v_mul_lo_u32 v2, v2, s26
	v_add_u32_e32 v0, 0x2000, v0
	v_add_lshl_u32 v130, v1, v14, 1
	v_add_lshl_u32 v132, v2, v1, 1
	v_ashrrev_i32_e32 v1, 31, v0
	v_lshrrev_b32_e32 v1, 22, v1
	v_add_u32_e32 v1, v0, v1
	v_ashrrev_i32_e32 v1, 10, v1
	s_add_u32 s6, s10, 0x22e80000
	v_mul_i32_i24_e32 v2, 0x400, v1
	s_addc_u32 s7, s11, 0
	v_sub_u32_e32 v0, v0, v2
	s_ashr_i32 s27, s26, 31
	v_lshrrev_b32_e32 v2, 4, v0
	s_lshl_b64 s[22:23], s[26:27], 9
	s_ashr_i32 s20, s65, 31
	v_bitop3_b32 v0, v2, v0, 32 bitop3:0x6c
	s_mul_i32 s20, s22, s20
	s_mul_hi_u32 s24, s22, s65
	v_ashrrev_i32_e32 v3, 31, v0
	s_add_i32 s20, s24, s20
	s_lshr_b64 s[24:25], s[26:27], 23
	v_lshrrev_b32_e32 v3, 26, v3
	s_mul_i32 s25, s24, s65
	v_lshlrev_b32_e32 v2, 3, v1
	v_add_u32_e32 v3, v0, v3
	s_add_i32 s38, s20, s25
	s_ashr_i32 s20, s62, 31
	v_and_b32_e32 v2, -16, v2
	v_ashrrev_i32_e32 v4, 6, v3
	s_mul_i32 s20, s22, s20
	s_mul_hi_u32 s25, s22, s62
	s_ashr_i32 s36, s33, 6
	v_add_u32_e32 v2, v4, v2
	v_lshlrev_b32_e32 v1, 5, v1
	v_and_b32_e32 v4, 3, v4
	s_add_i32 s20, s25, s20
	s_mul_i32 s24, s24, s62
	v_and_b32_e32 v15, 32, v1
	v_and_b32_e32 v1, 0xc0, v3
	v_and_or_b32 v4, v2, s14, v4
	s_ashr_i32 s37, s33, 8
	s_lshl_b64 s[14:15], s[26:27], 8
	s_lshl_b32 s18, s36, 10
	s_add_i32 s20, s20, s24
	s_mul_i32 s24, s22, s62
	v_sub_u32_e32 v0, v0, v1
	v_lshlrev_b32_e32 v1, 1, v2
	v_lshrrev_b32_e32 v3, 2, v2
	s_add_u32 s28, s12, s24
	v_ashrrev_i16_sdwa v0, v6, sext(v0) dst_sel:DWORD dst_unused:UNUSED_PAD src0_sel:DWORD src1_sel:BYTE_0
	v_and_b32_e32 v1, 24, v1
	v_and_b32_e32 v3, 4, v3
	s_addc_u32 s29, s13, s20
	s_add_i32 s20, s18, 0
	v_bfe_i32 v16, v0, 0, 16
	v_or3_b32 v1, v4, v3, v1
	s_add_i32 m0, s20, 0x10000
	v_add_u32_e32 v0, v15, v16
	v_mul_lo_u32 v1, v1, s26
	global_load_lds_dwordx4 v132, s[28:29]
	s_add_i32 m0, s20, 0x12000
	v_add_lshl_u32 v136, v1, v0, 1
	s_add_u32 s24, s28, s14
	global_load_lds_dwordx4 v136, s[28:29]
	s_addc_u32 s25, s29, s15
	s_add_i32 m0, s20, 0x14000
	s_mul_i32 s39, s22, s65
	global_load_lds_dwordx4 v132, s[24:25]
	s_add_i32 m0, s20, 0x16000
	s_add_u32 s46, s6, s39
	v_mov_b32_e32 v133, v129
	v_mov_b32_e32 v137, v129
	s_addc_u32 s47, s7, s38
	s_add_i32 s48, s20, 0x2000
	v_mul_lo_u32 v17, v2, s26
	v_lshl_add_u64 v[4:5], s[24:25], 0, v[132:133]
	v_lshl_add_u64 v[6:7], s[24:25], 0, v[136:137]
	global_load_lds_dwordx4 v136, s[24:25]
	s_mov_b32 m0, s20
	s_add_u32 s24, s46, s14
	v_add_lshl_u32 v134, v0, v17, 1
	global_load_lds_dwordx4 v130, s[46:47]
	s_mov_b32 m0, s48
	s_addc_u32 s25, s47, s15
	s_add_i32 s49, s20, 0x4000
	global_load_lds_dwordx4 v134, s[46:47]
	s_mov_b32 m0, s49
	s_add_i32 s50, s20, 0x6000
	global_load_lds_dwordx4 v130, s[24:25]
	s_mov_b32 m0, s50
	v_mov_b32_e32 v131, v129
	global_load_lds_dwordx4 v134, s[24:25]
	v_mov_b32_e32 v135, v129
	s_cmp_eq_u32 s37, 1
	v_lshl_add_u64 v[0:1], s[28:29], 0, v[132:133]
	v_lshl_add_u64 v[2:3], s[28:29], 0, v[136:137]
	v_lshl_add_u64 v[8:9], s[46:47], 0, v[130:131]
	v_lshl_add_u64 v[10:11], s[46:47], 0, v[134:135]
	s_cselect_b64 s[24:25], -1, 0
	s_add_i32 m0, s20, 0x18000
	v_lshl_add_u64 v[0:1], v[0:1], 0, s[34:35]
	global_load_lds_dwordx4 v[0:1], off
	v_lshl_add_u64 v[0:1], v[2:3], 0, s[34:35]
	s_add_i32 m0, s20, 0x1a000
	s_add_i32 s51, s20, 0x8000
	global_load_lds_dwordx4 v[0:1], off
	v_lshl_add_u64 v[0:1], v[8:9], 0, s[34:35]
	s_mov_b32 m0, s51
	s_add_i32 s52, s20, 0xa000
	global_load_lds_dwordx4 v[0:1], off
	v_lshl_add_u64 v[0:1], v[10:11], 0, s[34:35]
	s_mov_b32 m0, s52
	s_lshr_b32 s27, s27, 26
	global_load_lds_dwordx4 v[0:1], off
	s_add_i32 m0, s20, 0x1c000
	v_lshl_add_u64 v[0:1], v[4:5], 0, s[34:35]
	global_load_lds_dwordx4 v[0:1], off
	v_lshl_add_u64 v[0:1], v[6:7], 0, s[34:35]
	s_add_i32 m0, s20, 0x1e000
	s_add_i32 s27, s26, s27
	global_load_lds_dwordx4 v[0:1], off
	s_cmp_lg_u32 s37, 1
	s_cbranch_scc1 .Lpro_8
	s_barrier

.LBB0_2434:
	s_ashr_i32 s10, s7, 3
	s_and_b32 s11, s6, 0xe0
	v_or_b32_e32 v0, s11, v50
	s_lshl_b32 s12, s10, 6
	v_lshlrev_b32_e32 v128, 13, v0
	v_or_b32_e32 v0, s12, v50
	v_ashrrev_i32_e32 v1, 31, v0
	v_lshlrev_b64 v[2:3], 13, v[0:1]
	v_or_b32_e32 v0, 32, v0
	v_ashrrev_i32_e32 v1, 31, v0
	v_add_u32_e32 v38, s11, v52
	v_lshlrev_b64 v[0:1], 13, v[0:1]
	v_ashrrev_i32_e32 v39, 31, v38
	v_lshl_add_u64 v[46:47], v[34:35], 0, v[2:3]
	v_lshl_add_u64 v[48:49], v[34:35], 0, v[0:1]
	v_or_b32_e32 v0, s12, v144
	v_lshlrev_b64 v[2:3], 11, v[38:39]
	v_lshl_add_u64 v[2:3], s[0:1], 0, v[2:3]
	v_ashrrev_i32_e32 v1, 31, v0
	v_lshl_add_u64 v[36:37], v[0:1], 1, v[2:3]
	global_load_dwordx2 v[146:147], v[36:37], off
	v_lshl_add_u64 v[44:45], v[32:33], 0, v[128:129]
	global_load_dwordx4 v[16:19], v[44:45], off
	global_load_dwordx4 v[0:3], v[46:47], off
	global_load_dwordx4 v[20:23], v[48:49], off
	global_load_dwordx4 v[54:57], v[44:45], off offset:32
	global_load_dwordx4 v[58:61], v[46:47], off offset:32
	global_load_dwordx4 v[62:65], v[48:49], off offset:32
	global_load_dwordx4 v[66:69], v[44:45], off offset:64
	global_load_dwordx4 v[70:73], v[46:47], off offset:64
	global_load_dwordx4 v[74:77], v[48:49], off offset:64
	global_load_dwordx4 v[78:81], v[44:45], off offset:96
	global_load_dwordx4 v[82:85], v[46:47], off offset:96
	global_load_dwordx4 v[86:89], v[48:49], off offset:96
	global_load_dwordx4 v[90:93], v[44:45], off offset:128
	global_load_dwordx4 v[94:97], v[46:47], off offset:128
	global_load_dwordx4 v[98:101], v[48:49], off offset:128
	global_load_dwordx4 v[102:105], v[44:45], off offset:160
	global_load_dwordx4 v[106:109], v[46:47], off offset:160
	global_load_dwordx4 v[110:113], v[48:49], off offset:160
	global_load_dwordx4 v[114:117], v[44:45], off offset:192
	global_load_dwordx4 v[118:121], v[46:47], off offset:192
	global_load_dwordx4 v[122:125], v[48:49], off offset:192
	global_load_dwordx4 v[130:133], v[44:45], off offset:224
	global_load_dwordx4 v[134:137], v[46:47], off offset:224
	global_load_dwordx4 v[138:141], v[48:49], off offset:224
	s_waitcnt vmcnt(24)
	v_and_b32_e32 v41, 0xffff0000, v146
	v_lshlrev_b32_e32 v40, 16, v146
	v_and_b32_e32 v43, 0xffff0000, v147
	v_lshlrev_b32_e32 v42, 16, v147
	s_waitcnt vmcnt(22) lgkmcnt(0)
	v_mfma_f32_32x32x16_bf16 v[0:15], v[16:19], v[0:3], 0
	s_waitcnt vmcnt(21)
	v_mfma_f32_32x32x16_bf16 v[16:31], v[16:19], v[20:23], 0
	s_waitcnt vmcnt(19)
	v_mfma_f32_32x32x16_bf16 v[0:15], v[54:57], v[58:61], v[0:15]
	s_waitcnt vmcnt(18)
	v_mfma_f32_32x32x16_bf16 v[16:31], v[54:57], v[62:65], v[16:31]
	s_waitcnt vmcnt(16)
	v_mfma_f32_32x32x16_bf16 v[0:15], v[66:69], v[70:73], v[0:15]
	s_waitcnt vmcnt(15)
	v_mfma_f32_32x32x16_bf16 v[16:31], v[66:69], v[74:77], v[16:31]
	s_waitcnt vmcnt(13)
	v_mfma_f32_32x32x16_bf16 v[0:15], v[78:81], v[82:85], v[0:15]
	s_waitcnt vmcnt(12)
	v_mfma_f32_32x32x16_bf16 v[16:31], v[78:81], v[86:89], v[16:31]
	s_waitcnt vmcnt(10)
	v_mfma_f32_32x32x16_bf16 v[0:15], v[90:93], v[94:97], v[0:15]
	s_waitcnt vmcnt(9)
	v_mfma_f32_32x32x16_bf16 v[16:31], v[90:93], v[98:101], v[16:31]
	s_waitcnt vmcnt(7)
	v_mfma_f32_32x32x16_bf16 v[0:15], v[102:105], v[106:109], v[0:15]
	s_waitcnt vmcnt(6)
	v_mfma_f32_32x32x16_bf16 v[16:31], v[102:105], v[110:113], v[16:31]
	s_waitcnt vmcnt(4)
	v_mfma_f32_32x32x16_bf16 v[0:15], v[114:117], v[118:121], v[0:15]
	s_waitcnt vmcnt(3)
	v_mfma_f32_32x32x16_bf16 v[16:31], v[114:117], v[122:125], v[16:31]
	s_waitcnt vmcnt(1)
	v_mfma_f32_32x32x16_bf16 v[0:15], v[130:133], v[134:137], v[0:15]
	s_waitcnt vmcnt(0)
	v_mfma_f32_32x32x16_bf16 v[16:31], v[130:133], v[138:141], v[16:31]
	global_load_dwordx4 v[54:57], v[44:45], off offset:256
	global_load_dwordx4 v[58:61], v[44:45], off offset:288
	global_load_dwordx4 v[62:65], v[46:47], off offset:256
	global_load_dwordx4 v[66:69], v[46:47], off offset:288
	global_load_dwordx4 v[70:73], v[48:49], off offset:256
	global_load_dwordx4 v[74:77], v[48:49], off offset:288
	global_load_dwordx4 v[78:81], v[44:45], off offset:320
	global_load_dwordx4 v[82:85], v[44:45], off offset:352
	global_load_dwordx4 v[86:89], v[46:47], off offset:320
	global_load_dwordx4 v[90:93], v[46:47], off offset:352
	global_load_dwordx4 v[94:97], v[48:49], off offset:320
	global_load_dwordx4 v[98:101], v[48:49], off offset:352
	global_load_dwordx4 v[102:105], v[44:45], off offset:384
	global_load_dwordx4 v[106:109], v[44:45], off offset:416
	global_load_dwordx4 v[110:113], v[46:47], off offset:384
	global_load_dwordx4 v[114:117], v[46:47], off offset:416
	global_load_dwordx4 v[118:121], v[48:49], off offset:384
	global_load_dwordx4 v[122:125], v[48:49], off offset:416
	global_load_dwordx4 v[130:133], v[44:45], off offset:448
	global_load_dwordx4 v[134:137], v[44:45], off offset:480
	global_load_dwordx4 v[138:141], v[46:47], off offset:448
	global_load_dwordx4 v[146:149], v[46:47], off offset:480
	global_load_dwordx4 v[150:153], v[48:49], off offset:448
	global_load_dwordx4 v[154:157], v[48:49], off offset:480
	s_waitcnt vmcnt(21)
	v_mfma_f32_32x32x16_bf16 v[0:15], v[54:57], v[62:65], v[0:15]
	s_waitcnt vmcnt(19)
	v_mfma_f32_32x32x16_bf16 v[16:31], v[54:57], v[70:73], v[16:31]
	v_mfma_f32_32x32x16_bf16 v[0:15], v[58:61], v[66:69], v[0:15]
	s_waitcnt vmcnt(18)
	v_mfma_f32_32x32x16_bf16 v[16:31], v[58:61], v[74:77], v[16:31]
	s_waitcnt vmcnt(15)
	v_mfma_f32_32x32x16_bf16 v[0:15], v[78:81], v[86:89], v[0:15]
	s_waitcnt vmcnt(13)
	v_mfma_f32_32x32x16_bf16 v[16:31], v[78:81], v[94:97], v[16:31]
	v_mfma_f32_32x32x16_bf16 v[0:15], v[82:85], v[90:93], v[0:15]
	s_waitcnt vmcnt(12)
	v_mfma_f32_32x32x16_bf16 v[16:31], v[82:85], v[98:101], v[16:31]
	s_waitcnt vmcnt(9)
	v_mfma_f32_32x32x16_bf16 v[0:15], v[102:105], v[110:113], v[0:15]
	s_waitcnt vmcnt(7)
	v_mfma_f32_32x32x16_bf16 v[16:31], v[102:105], v[118:121], v[16:31]
	v_mfma_f32_32x32x16_bf16 v[0:15], v[106:109], v[114:117], v[0:15]
	s_waitcnt vmcnt(6)
	v_mfma_f32_32x32x16_bf16 v[16:31], v[106:109], v[122:125], v[16:31]
	s_waitcnt vmcnt(3)
	v_mfma_f32_32x32x16_bf16 v[0:15], v[130:133], v[138:141], v[0:15]
	s_waitcnt vmcnt(1)
	v_mfma_f32_32x32x16_bf16 v[16:31], v[130:133], v[150:153], v[16:31]
	v_mfma_f32_32x32x16_bf16 v[0:15], v[134:137], v[146:149], v[0:15]
	s_waitcnt vmcnt(0)
	v_mfma_f32_32x32x16_bf16 v[16:31], v[134:137], v[154:157], v[16:31]
	global_load_dwordx4 v[54:57], v[44:45], off offset:512
	global_load_dwordx4 v[58:61], v[44:45], off offset:544
	global_load_dwordx4 v[62:65], v[46:47], off offset:512
	global_load_dwordx4 v[66:69], v[46:47], off offset:544
	global_load_dwordx4 v[70:73], v[48:49], off offset:512
	global_load_dwordx4 v[74:77], v[48:49], off offset:544
	global_load_dwordx4 v[78:81], v[44:45], off offset:576
	global_load_dwordx4 v[82:85], v[44:45], off offset:608
	global_load_dwordx4 v[86:89], v[46:47], off offset:576
	global_load_dwordx4 v[90:93], v[46:47], off offset:608
	global_load_dwordx4 v[94:97], v[48:49], off offset:576
	global_load_dwordx4 v[98:101], v[48:49], off offset:608
	global_load_dwordx4 v[102:105], v[44:45], off offset:640
	global_load_dwordx4 v[106:109], v[44:45], off offset:672
	global_load_dwordx4 v[110:113], v[46:47], off offset:640
	global_load_dwordx4 v[114:117], v[46:47], off offset:672
	global_load_dwordx4 v[118:121], v[48:49], off offset:640
	global_load_dwordx4 v[122:125], v[48:49], off offset:672
	global_load_dwordx4 v[130:133], v[44:45], off offset:704
	global_load_dwordx4 v[134:137], v[44:45], off offset:736
	global_load_dwordx4 v[138:141], v[46:47], off offset:704
	global_load_dwordx4 v[146:149], v[46:47], off offset:736
	global_load_dwordx4 v[150:153], v[48:49], off offset:704
	global_load_dwordx4 v[154:157], v[48:49], off offset:736
	s_waitcnt vmcnt(21)
	v_mfma_f32_32x32x16_bf16 v[0:15], v[54:57], v[62:65], v[0:15]
	s_waitcnt vmcnt(19)
	v_mfma_f32_32x32x16_bf16 v[16:31], v[54:57], v[70:73], v[16:31]
	v_mfma_f32_32x32x16_bf16 v[0:15], v[58:61], v[66:69], v[0:15]
	s_waitcnt vmcnt(18)
	v_mfma_f32_32x32x16_bf16 v[16:31], v[58:61], v[74:77], v[16:31]
	s_waitcnt vmcnt(15)
	v_mfma_f32_32x32x16_bf16 v[0:15], v[78:81], v[86:89], v[0:15]
	s_waitcnt vmcnt(13)
	v_mfma_f32_32x32x16_bf16 v[16:31], v[78:81], v[94:97], v[16:31]
	v_mfma_f32_32x32x16_bf16 v[0:15], v[82:85], v[90:93], v[0:15]
	s_waitcnt vmcnt(12)
	v_mfma_f32_32x32x16_bf16 v[16:31], v[82:85], v[98:101], v[16:31]
	s_waitcnt vmcnt(9)
	v_mfma_f32_32x32x16_bf16 v[0:15], v[102:105], v[110:113], v[0:15]
	s_waitcnt vmcnt(7)
	v_mfma_f32_32x32x16_bf16 v[16:31], v[102:105], v[118:121], v[16:31]
	v_mfma_f32_32x32x16_bf16 v[0:15], v[106:109], v[114:117], v[0:15]
	s_waitcnt vmcnt(6)
	v_mfma_f32_32x32x16_bf16 v[16:31], v[106:109], v[122:125], v[16:31]
	s_waitcnt vmcnt(3)
	v_mfma_f32_32x32x16_bf16 v[0:15], v[130:133], v[138:141], v[0:15]
	s_waitcnt vmcnt(1)
	v_mfma_f32_32x32x16_bf16 v[16:31], v[130:133], v[150:153], v[16:31]
	v_mfma_f32_32x32x16_bf16 v[0:15], v[134:137], v[146:149], v[0:15]
	s_waitcnt vmcnt(0)
	v_mfma_f32_32x32x16_bf16 v[16:31], v[134:137], v[154:157], v[16:31]
	global_load_dwordx4 v[54:57], v[44:45], off offset:768
	global_load_dwordx4 v[58:61], v[44:45], off offset:800
	global_load_dwordx4 v[62:65], v[46:47], off offset:768
	global_load_dwordx4 v[66:69], v[46:47], off offset:800
	global_load_dwordx4 v[70:73], v[48:49], off offset:768
	global_load_dwordx4 v[74:77], v[48:49], off offset:800
	global_load_dwordx4 v[78:81], v[44:45], off offset:832
	global_load_dwordx4 v[82:85], v[44:45], off offset:864
	global_load_dwordx4 v[86:89], v[46:47], off offset:832
	global_load_dwordx4 v[90:93], v[46:47], off offset:864
	global_load_dwordx4 v[94:97], v[48:49], off offset:832
	global_load_dwordx4 v[98:101], v[48:49], off offset:864
	global_load_dwordx4 v[102:105], v[44:45], off offset:896
	global_load_dwordx4 v[106:109], v[44:45], off offset:928
	global_load_dwordx4 v[110:113], v[46:47], off offset:896
	global_load_dwordx4 v[114:117], v[46:47], off offset:928
	global_load_dwordx4 v[118:121], v[48:49], off offset:896
	global_load_dwordx4 v[122:125], v[48:49], off offset:928
	global_load_dwordx4 v[130:133], v[44:45], off offset:960
	global_load_dwordx4 v[134:137], v[44:45], off offset:992
	global_load_dwordx4 v[138:141], v[46:47], off offset:960
	s_nop 0
	global_load_dwordx4 v[44:47], v[46:47], off offset:992
	s_nop 0
	global_load_dwordx4 v[146:149], v[48:49], off offset:960
	global_load_dwordx4 v[150:153], v[48:49], off offset:992
	s_waitcnt vmcnt(21)
	v_mfma_f32_32x32x16_bf16 v[0:15], v[54:57], v[62:65], v[0:15]
	s_waitcnt vmcnt(19)
	v_mfma_f32_32x32x16_bf16 v[16:31], v[54:57], v[70:73], v[16:31]
	v_mfma_f32_32x32x16_bf16 v[0:15], v[58:61], v[66:69], v[0:15]
	s_waitcnt vmcnt(18)
	v_mfma_f32_32x32x16_bf16 v[16:31], v[58:61], v[74:77], v[16:31]
	s_waitcnt vmcnt(15)
	v_mfma_f32_32x32x16_bf16 v[0:15], v[78:81], v[86:89], v[0:15]
	s_waitcnt vmcnt(13)
	v_mfma_f32_32x32x16_bf16 v[16:31], v[78:81], v[94:97], v[16:31]
	v_mfma_f32_32x32x16_bf16 v[0:15], v[82:85], v[90:93], v[0:15]
	s_waitcnt vmcnt(12)
	v_mfma_f32_32x32x16_bf16 v[16:31], v[82:85], v[98:101], v[16:31]
	s_waitcnt vmcnt(9)
	v_mfma_f32_32x32x16_bf16 v[0:15], v[102:105], v[110:113], v[0:15]
	s_waitcnt vmcnt(7)
	v_mfma_f32_32x32x16_bf16 v[16:31], v[102:105], v[118:121], v[16:31]
	v_mfma_f32_32x32x16_bf16 v[0:15], v[106:109], v[114:117], v[0:15]
	s_waitcnt vmcnt(6)
	v_mfma_f32_32x32x16_bf16 v[16:31], v[106:109], v[122:125], v[16:31]
	s_waitcnt vmcnt(3)
	v_mfma_f32_32x32x16_bf16 v[0:15], v[130:133], v[138:141], v[0:15]
	s_waitcnt vmcnt(1)
	v_mfma_f32_32x32x16_bf16 v[16:31], v[130:133], v[146:149], v[16:31]
	v_mfma_f32_32x32x16_bf16 v[0:15], v[134:137], v[44:47], v[0:15]
	s_waitcnt vmcnt(0)
	v_mfma_f32_32x32x16_bf16 v[16:31], v[134:137], v[150:153], v[16:31]
	s_nop 11
	ds_write2_b32 v51, v0, v16 offset1:32
	ds_write2_b32 v51, v1, v17 offset0:65 offset1:97
	ds_write2_b32 v51, v2, v18 offset0:130 offset1:162
	ds_write2_b32 v51, v3, v19 offset0:195 offset1:227
	v_add_u32_e32 v0, 0x800, v51
	ds_write2_b32 v0, v4, v20 offset0:8 offset1:40
	ds_write2_b32 v0, v5, v21 offset0:73 offset1:105
	ds_write2_b32 v0, v6, v22 offset0:138 offset1:170
	ds_write2_b32 v0, v7, v23 offset0:203 offset1:235
	v_add_u32_e32 v0, 0x1000, v51
	ds_write2_b32 v0, v8, v24 offset0:16 offset1:48
	ds_write2_b32 v0, v9, v25 offset0:81 offset1:113
	ds_write2_b32 v0, v10, v26 offset0:146 offset1:178
	ds_write2_b32 v0, v11, v27 offset0:211 offset1:243
	v_add_u32_e32 v0, 0x1800, v51
	ds_write2_b32 v0, v12, v28 offset0:24 offset1:56
	ds_write2_b32 v0, v13, v29 offset0:89 offset1:121
	ds_write2_b32 v0, v14, v30 offset0:154 offset1:186
	ds_write2_b32 v0, v15, v31 offset0:219 offset1:251
	s_waitcnt lgkmcnt(0)
	s_barrier
	v_add_u32_e32 v10, 0x2080, v53
	v_add_u32_e32 v12, 0x4100, v53
	v_add_u32_e32 v0, 0x6180, v53
	v_add_u32_e32 v2, 0x8200, v53
	v_add_u32_e32 v4, 0xa280, v53
	v_add_u32_e32 v6, 0xc300, v53
	ds_read2_b32 v[0:1], v0 offset1:1
	ds_read2_b32 v[2:3], v2 offset1:1
	ds_read2_b32 v[4:5], v4 offset1:1
	ds_read2_b32 v[6:7], v6 offset1:1
	ds_read2_b32 v[8:9], v53 offset1:1
	ds_read2_b32 v[10:11], v10 offset1:1
	ds_read2_b32 v[12:13], v12 offset1:1
	ds_read2_b32 v[14:15], v53 offset0:2 offset1:3
	v_add_u32_e32 v16, 0xe380, v53
	v_add_u32_e32 v18, 0x2088, v53
	v_add_u32_e32 v20, 0x4108, v53
	v_add_u32_e32 v22, 0x6188, v53
	ds_read2_b32 v[16:17], v16 offset1:1
	ds_read2_b32 v[18:19], v18 offset1:1
	ds_read2_b32 v[20:21], v20 offset1:1
	ds_read2_b32 v[22:23], v22 offset1:1
	s_waitcnt lgkmcnt(4)
	v_pk_add_f32 v[14:15], v[14:15], 0 op_sel_hi:[1,0]
	v_pk_add_f32 v[8:9], v[8:9], 0 op_sel_hi:[1,0]
	v_add_u32_e32 v24, 0x8208, v53
	v_add_u32_e32 v26, 0xa288, v53
	v_add_u32_e32 v28, 0xc308, v53
	v_add_u32_e32 v30, 0xe388, v53
	v_pk_add_f32 v[8:9], v[8:9], v[10:11]
	s_waitcnt lgkmcnt(2)
	v_pk_add_f32 v[10:11], v[14:15], v[18:19]
	ds_read2_b32 v[24:25], v24 offset1:1
	ds_read2_b32 v[26:27], v26 offset1:1
	ds_read2_b32 v[28:29], v28 offset1:1
	ds_read2_b32 v[30:31], v30 offset1:1
	s_waitcnt lgkmcnt(5)
	v_pk_add_f32 v[10:11], v[10:11], v[20:21]
	v_pk_add_f32 v[8:9], v[8:9], v[12:13]
	s_waitcnt lgkmcnt(0)
	s_barrier
	s_nop 0
	v_pk_add_f32 v[0:1], v[8:9], v[0:1]
	s_waitcnt lgkmcnt(4)
	v_pk_add_f32 v[8:9], v[10:11], v[22:23]
	v_pk_add_f32 v[0:1], v[0:1], v[2:3]
	s_waitcnt lgkmcnt(3)
	v_pk_add_f32 v[8:9], v[8:9], v[24:25]
	v_pk_add_f32 v[0:1], v[0:1], v[4:5]
	s_waitcnt lgkmcnt(2)
	v_pk_add_f32 v[2:3], v[8:9], v[26:27]
	v_pk_add_f32 v[0:1], v[0:1], v[6:7]
	s_waitcnt lgkmcnt(1)
	v_pk_add_f32 v[2:3], v[2:3], v[28:29]
	v_pk_add_f32 v[4:5], v[0:1], v[16:17]
	s_waitcnt lgkmcnt(0)
	v_pk_add_f32 v[0:1], v[2:3], v[30:31]
	v_pk_add_f32 v[2:3], v[4:5], v[40:41]
	v_pk_add_f32 v[0:1], v[0:1], v[42:43]
	v_mul_f32_e32 v4, v3, v3
	v_mul_f32_e32 v5, v1, v1
	v_fmac_f32_e32 v4, v2, v2
	v_fmac_f32_e32 v5, v0, v0
	v_add_f32_e32 v4, v4, v5
	ds_swizzle_b32 v5, v4 offset:swizzle(SWAP,1)
	s_waitcnt lgkmcnt(0)
	v_add_f32_e32 v4, v4, v5
	ds_swizzle_b32 v5, v4 offset:swizzle(SWAP,2)
	s_waitcnt lgkmcnt(0)
	v_add_f32_e32 v4, v4, v5
	ds_swizzle_b32 v5, v4 offset:swizzle(SWAP,4)
	s_waitcnt lgkmcnt(0)
	v_add_f32_e32 v4, v4, v5
	ds_swizzle_b32 v5, v4 offset:swizzle(SWAP,8)
	s_and_saveexec_b64 s[12:13], vcc
	s_cbranch_execz .LBB0_2433
	v_lshlrev_b64 v[6:7], 6, v[38:39]
	v_lshl_add_u64 v[6:7], s[2:3], 0, v[6:7]
	s_ashr_i32 s11, s10, 31
	v_lshl_add_u64 v[6:7], s[10:11], 2, v[6:7]
	s_waitcnt lgkmcnt(0)
	v_add_f32_e32 v4, v4, v5
	global_store_dword v[6:7], v4, off
	s_branch .LBB0_2433
